# ssq (row rstd) loads of G2/G3 epilogues prefetched once per unit instead of 8 serialized load-wait round trips; stacked on conv-weight prefetch + batched residual loads + fast MLA softmax loop
# baseline (speedup 1.0000x reference)
; #define PG8_STAGE(bufoff, gbase, voff) do { _Pragma("unroll") for (int _i = 0; _i < 2; ++_i) \
;         __builtin_amdgcn_global_load_lds((const unsigned*)((const char*)(gbase) + (voff)[_i]), (LAS unsigned*)(lds + (bufoff) + ldsw + _i * 8192), 16, 0, 0); } while (0)
; #define PG8_LDA(dst, b, h) do { _Pragma("unroll") for (int m = 0; m < 4; ++m) _Pragma("unroll") for (int k = 0; k < 2; ++k) dst[m][k] = *(const LAS bf16x8*)(lds + PG8_SA(b, h) + aoff + m * 2048 + k * 1024); } while (0)
; #define PG8_LDB(dst, b, h) do { _Pragma("unroll") for (int n = 0; n < 2; ++n) _Pragma("unroll") for (int k = 0; k < 2; ++k) dst[n][k] = *(const LAS bf16x8*)(lds + PG8_SB(b, h) + boff + n * 2048 + k * 1024); } while (0)
; #define PG8_MMA(ai, bj, At, Bt) do { __builtin_amdgcn_s_setprio(1); _Pragma("unroll") for (int m = 0; m < 4; ++m) _Pragma("unroll") for (int n = 0; n < 2; ++n) _Pragma("unroll") for (int k = 0; k < 2; ++k) \
;         acc[ai][bj][m][n] = __builtin_amdgcn_mfma_f32_16x16x32_bf16(Bt[n][k], At[m][k], acc[ai][bj][m][n], 0, 0, 0); __builtin_amdgcn_s_setprio(0); } while (0)
; #define PG8_WAIT_L(n) asm volatile("s_waitcnt lgkmcnt(" #n ")" ::: "memory")
; #define PG8_BAR __builtin_amdgcn_s_barrier()
; #define PG8_SCHED __builtin_amdgcn_sched_barrier(0)
; template <class Epi, class SchedT>
; DI void gemm_phase(LAS unsigned char* lds, const Gemm g, const SchedT& S, const Epi& E) {
;     ...
;             PG8_LDB(B0, 0, 0); PG8_SCHED; PG8_LDA(At, 0, 0); PG8_STAGE(PG8_SA(1, 1), a1 + hstepA, voffA);
;             PG8_WAIT_L(8); PG8_BAR; PG8_WAIT_L(0); PG8_MMA(0, 0, At, B0); PG8_BAR; PG8_SCHED;
;             PG8_LDB(B1, 0, 1); PG8_STAGE(PG8_SB(0, 0), b2, voffB);
;             PG8_BAR; PG8_WAIT_L(0); PG8_MMA(0, 1, At, B1); PG8_BAR;
;             PG8_LDA(At, 0, 1); PG8_STAGE(PG8_SA(0, 0), a2, voffA);
;             PG8_BAR; PG8_WAIT_L(0); PG8_MMA(1, 0, At, B0); PG8_BAR; PG8_SCHED;
.LBB0_643:
	s_add_u32 s24, s0, 0xfff30080
	s_addc_u32 s25, s1, -1
	s_add_i32 s39, 0, 0x10000
	v_add_u32_e32 v152, s39, v146
	ds_read_b128 v[136:139], v152
	ds_read_b128 v[140:143], v152 offset:1024
	ds_read_b128 v[148:151], v152 offset:2048
	ds_read_b128 v[152:155], v152 offset:3072
	s_cmp_eq_u32 s38, 4
	s_cselect_b32 s27, s21, s25
	s_cselect_b32 s26, s20, s24
	s_cselect_b32 s25, s5, s33
	s_cselect_b32 s24, s19, s29
	v_lshl_add_u64 v[176:177], s[0:1], 0, v[0:1]
	s_add_i32 m0, s44, 0xc000
	ds_read_b128 v[156:159], v147
	ds_read_b128 v[160:163], v147 offset:1024
	ds_read_b128 v[164:167], v147 offset:2048
	ds_read_b128 v[168:171], v147 offset:3072
	ds_read_b128 v[172:175], v147 offset:4096
	ds_read_b128 v[184:187], v147 offset:5120
	ds_read_b128 v[188:191], v147 offset:6144
	ds_read_b128 v[202:205], v147 offset:7168
	global_load_lds_dwordx4 v[176:177], off
	v_lshl_add_u64 v[176:177], s[0:1], 0, v[132:133]
	s_add_i32 m0, s44, 0xe000
	s_nop 0
	global_load_lds_dwordx4 v[176:177], off
	s_waitcnt lgkmcnt(8)
	s_barrier
	s_waitcnt lgkmcnt(0)
	s_setprio 1
	s_waitcnt lgkmcnt(0)
	v_mfma_f32_16x16x32_bf16 v[126:129], v[136:139], v[156:159], v[126:129]
	v_mfma_f32_16x16x32_bf16 v[122:125], v[148:151], v[156:159], v[122:125]
	v_mfma_f32_16x16x32_bf16 v[110:113], v[136:139], v[164:167], v[110:113]
	v_mfma_f32_16x16x32_bf16 v[106:109], v[148:151], v[164:167], v[106:109]
	v_mfma_f32_16x16x32_bf16 v[94:97], v[136:139], v[172:175], v[94:97]
	v_mfma_f32_16x16x32_bf16 v[90:93], v[148:151], v[172:175], v[90:93]
	v_mfma_f32_16x16x32_bf16 v[78:81], v[136:139], v[188:191], v[78:81]
	v_mfma_f32_16x16x32_bf16 v[74:77], v[148:151], v[188:191], v[74:77]
	v_mfma_f32_16x16x32_bf16 v[126:129], v[140:143], v[160:163], v[126:129]
	v_mfma_f32_16x16x32_bf16 v[122:125], v[152:155], v[160:163], v[122:125]
	v_mfma_f32_16x16x32_bf16 v[110:113], v[140:143], v[168:171], v[110:113]
	v_mfma_f32_16x16x32_bf16 v[106:109], v[152:155], v[168:171], v[106:109]
	v_mfma_f32_16x16x32_bf16 v[94:97], v[140:143], v[184:187], v[94:97]
	v_mfma_f32_16x16x32_bf16 v[90:93], v[152:155], v[184:187], v[90:93]
	v_mfma_f32_16x16x32_bf16 v[78:81], v[140:143], v[202:205], v[78:81]
	v_mfma_f32_16x16x32_bf16 v[74:77], v[152:155], v[202:205], v[74:77]
	s_setprio 0
	s_barrier
	s_add_i32 s46, 0, 0x14000
	v_add_u32_e32 v176, s46, v146
	s_add_i32 s39, s39, s36
	ds_read_b128 v[206:209], v176
	ds_read_b128 v[210:213], v176 offset:1024
	ds_read_b128 v[214:217], v176 offset:2048
	ds_read_b128 v[218:221], v176 offset:3072
	v_lshl_add_u64 v[176:177], s[24:25], 0, v[130:131]
	s_mov_b32 m0, s39
	v_lshl_add_u64 v[178:179], s[24:25], 0, v[134:135]
	global_load_lds_dwordx4 v[176:177], off
	s_add_i32 m0, s39, 0x2000
	s_nop 0
	global_load_lds_dwordx4 v[178:179], off
	s_barrier
	s_waitcnt lgkmcnt(0)
	s_setprio 1
	s_waitcnt lgkmcnt(0)
	v_mfma_f32_16x16x32_bf16 v[118:121], v[206:209], v[156:159], v[118:121]
	v_mfma_f32_16x16x32_bf16 v[114:117], v[214:217], v[156:159], v[114:117]
	v_mfma_f32_16x16x32_bf16 v[102:105], v[206:209], v[164:167], v[102:105]
	v_mfma_f32_16x16x32_bf16 v[98:101], v[214:217], v[164:167], v[98:101]
	v_mfma_f32_16x16x32_bf16 v[86:89], v[206:209], v[172:175], v[86:89]
	v_mfma_f32_16x16x32_bf16 v[82:85], v[214:217], v[172:175], v[82:85]
	v_mfma_f32_16x16x32_bf16 v[70:73], v[206:209], v[188:191], v[70:73]
	v_mfma_f32_16x16x32_bf16 v[66:69], v[214:217], v[188:191], v[66:69]
	v_mfma_f32_16x16x32_bf16 v[118:121], v[210:213], v[160:163], v[118:121]
	v_mfma_f32_16x16x32_bf16 v[114:117], v[218:221], v[160:163], v[114:117]
	v_mfma_f32_16x16x32_bf16 v[102:105], v[210:213], v[168:171], v[102:105]
	v_mfma_f32_16x16x32_bf16 v[98:101], v[218:221], v[168:171], v[98:101]
	v_mfma_f32_16x16x32_bf16 v[86:89], v[210:213], v[184:187], v[86:89]
	v_mfma_f32_16x16x32_bf16 v[82:85], v[218:221], v[184:187], v[82:85]
	v_mfma_f32_16x16x32_bf16 v[70:73], v[210:213], v[202:205], v[70:73]
	v_mfma_f32_16x16x32_bf16 v[66:69], v[218:221], v[202:205], v[66:69]
	s_setprio 0
	s_mov_b32 m0, s44
	v_lshl_add_u64 v[180:181], s[26:27], 0, v[0:1]
	s_barrier
	ds_read_b128 v[156:159], v147 offset:16384
	ds_read_b128 v[160:163], v147 offset:17408
	ds_read_b128 v[164:167], v147 offset:18432
	ds_read_b128 v[168:171], v147 offset:19456
	ds_read_b128 v[172:175], v147 offset:20480
	ds_read_b128 v[184:187], v147 offset:21504
	ds_read_b128 v[188:191], v147 offset:22528
	ds_read_b128 v[202:205], v147 offset:23552
	global_load_lds_dwordx4 v[180:181], off
	v_lshl_add_u64 v[222:223], s[26:27], 0, v[132:133]
	s_mov_b32 m0, s45
	s_nop 0
	global_load_lds_dwordx4 v[222:223], off
	s_barrier
	s_waitcnt lgkmcnt(0)
	s_setprio 1
	s_waitcnt lgkmcnt(0)
	v_mfma_f32_16x16x32_bf16 v[62:65], v[136:139], v[156:159], v[62:65]
	v_mfma_f32_16x16x32_bf16 v[58:61], v[148:151], v[156:159], v[58:61]
	v_mfma_f32_16x16x32_bf16 v[46:49], v[136:139], v[164:167], v[46:49]
	v_mfma_f32_16x16x32_bf16 v[42:45], v[148:151], v[164:167], v[42:45]
	v_mfma_f32_16x16x32_bf16 v[30:33], v[136:139], v[172:175], v[30:33]
	v_mfma_f32_16x16x32_bf16 v[26:29], v[148:151], v[172:175], v[26:29]
	v_mfma_f32_16x16x32_bf16 v[14:17], v[136:139], v[188:191], v[14:17]
	v_mfma_f32_16x16x32_bf16 v[10:13], v[148:151], v[188:191], v[10:13]
	v_mfma_f32_16x16x32_bf16 v[62:65], v[140:143], v[160:163], v[62:65]
	v_mfma_f32_16x16x32_bf16 v[58:61], v[152:155], v[160:163], v[58:61]
	v_mfma_f32_16x16x32_bf16 v[46:49], v[140:143], v[168:171], v[46:49]
	v_mfma_f32_16x16x32_bf16 v[42:45], v[152:155], v[168:171], v[42:45]
	v_mfma_f32_16x16x32_bf16 v[30:33], v[140:143], v[184:187], v[30:33]
	v_mfma_f32_16x16x32_bf16 v[26:29], v[152:155], v[184:187], v[26:29]
	v_mfma_f32_16x16x32_bf16 v[14:17], v[140:143], v[202:205], v[14:17]
	v_mfma_f32_16x16x32_bf16 v[10:13], v[152:155], v[202:205], v[10:13]
	s_setprio 0
	s_barrier
; #define PG8_STAGE(bufoff, gbase, voff) do { _Pragma("unroll") for (int _i = 0; _i < 2; ++_i) \
;         __builtin_amdgcn_global_load_lds((const unsigned*)((const char*)(gbase) + (voff)[_i]), (LAS unsigned*)(lds + (bufoff) + ldsw + _i * 8192), 16, 0, 0); } while (0)
; #define PG8_LDA(dst, b, h) do { _Pragma("unroll") for (int m = 0; m < 4; ++m) _Pragma("unroll") for (int k = 0; k < 2; ++k) dst[m][k] = *(const LAS bf16x8*)(lds + PG8_SA(b, h) + aoff + m * 2048 + k * 1024); } while (0)
; #define PG8_LDB(dst, b, h) do { _Pragma("unroll") for (int n = 0; n < 2; ++n) _Pragma("unroll") for (int k = 0; k < 2; ++k) dst[n][k] = *(const LAS bf16x8*)(lds + PG8_SB(b, h) + boff + n * 2048 + k * 1024); } while (0)
; #define PG8_MMA(ai, bj, At, Bt) do { __builtin_amdgcn_s_setprio(1); _Pragma("unroll") for (int m = 0; m < 4; ++m) _Pragma("unroll") for (int n = 0; n < 2; ++n) _Pragma("unroll") for (int k = 0; k < 2; ++k) \
;         acc[ai][bj][m][n] = __builtin_amdgcn_mfma_f32_16x16x32_bf16(Bt[n][k], At[m][k], acc[ai][bj][m][n], 0, 0, 0); __builtin_amdgcn_s_setprio(0); } while (0)
; #define PG8_WAIT_V(n) asm volatile("s_waitcnt vmcnt(" #n ")" ::: "memory")
; #define PG8_WAIT_L(n) asm volatile("s_waitcnt lgkmcnt(" #n ")" ::: "memory")
; #define PG8_BAR __builtin_amdgcn_s_barrier()
; #define PG8_SCHED __builtin_amdgcn_sched_barrier(0)
; template <class Epi, class SchedT>
; DI void gemm_phase(LAS unsigned char* lds, const Gemm g, const SchedT& S, const Epi& E) {
;     ...
;             PG8_STAGE(PG8_SB(0, 1), b2 + hstepB, voffB);
;             PG8_WAIT_V(6); PG8_BAR; PG8_MMA(1, 1, At, B1); PG8_BAR;
;             PG8_LDB(B0, 1, 0); PG8_SCHED; PG8_LDA(At, 1, 0); PG8_STAGE(PG8_SA(0, 1), a2 + hstepA, voffA);
;             PG8_WAIT_L(8); PG8_BAR; PG8_WAIT_L(0); PG8_MMA(0, 0, At, B0); PG8_BAR; PG8_SCHED;
;             PG8_LDB(B1, 1, 1); PG8_STAGE(PG8_SB(1, 0), b3, voffB);
;             PG8_BAR; PG8_WAIT_L(0); PG8_MMA(0, 1, At, B1); PG8_BAR;
;             PG8_LDA(At, 1, 1); PG8_STAGE(PG8_SA(1, 0), a3, voffA);
;             PG8_BAR; PG8_WAIT_L(0); PG8_MMA(1, 0, At, B0); PG8_BAR; PG8_SCHED;
	s_add_u32 s66, s24, 0x20000
	s_addc_u32 s67, s25, 0
	s_add_i32 s39, s46, s36
	v_lshl_add_u64 v[136:137], s[66:67], 0, v[130:131]
	s_mov_b32 m0, s39
	s_nop 0
	global_load_lds_dwordx4 v[136:137], off
	v_lshl_add_u64 v[136:137], s[66:67], 0, v[134:135]
	s_add_i32 m0, s39, 0x2000
	s_nop 0
	global_load_lds_dwordx4 v[136:137], off
	s_waitcnt vmcnt(6)
	s_barrier
	s_setprio 1
	v_mfma_f32_16x16x32_bf16 v[54:57], v[206:209], v[156:159], v[54:57]
	v_mfma_f32_16x16x32_bf16 v[50:53], v[214:217], v[156:159], v[50:53]
	v_mfma_f32_16x16x32_bf16 v[38:41], v[206:209], v[164:167], v[38:41]
	v_mfma_f32_16x16x32_bf16 v[34:37], v[214:217], v[164:167], v[34:37]
	v_mfma_f32_16x16x32_bf16 v[22:25], v[206:209], v[172:175], v[22:25]
	v_mfma_f32_16x16x32_bf16 v[18:21], v[214:217], v[172:175], v[18:21]
	v_mfma_f32_16x16x32_bf16 v[6:9], v[206:209], v[188:191], v[6:9]
	v_mfma_f32_16x16x32_bf16 v[2:5], v[214:217], v[188:191], v[2:5]
	v_mfma_f32_16x16x32_bf16 v[54:57], v[210:213], v[160:163], v[54:57]
	v_mfma_f32_16x16x32_bf16 v[50:53], v[218:221], v[160:163], v[50:53]
	v_mfma_f32_16x16x32_bf16 v[38:41], v[210:213], v[168:171], v[38:41]
	v_mfma_f32_16x16x32_bf16 v[34:37], v[218:221], v[168:171], v[34:37]
	v_mfma_f32_16x16x32_bf16 v[22:25], v[210:213], v[184:187], v[22:25]
	v_mfma_f32_16x16x32_bf16 v[18:21], v[218:221], v[184:187], v[18:21]
	v_mfma_f32_16x16x32_bf16 v[6:9], v[210:213], v[202:205], v[6:9]
	v_mfma_f32_16x16x32_bf16 v[2:5], v[218:221], v[202:205], v[2:5]
	s_setprio 0
	s_add_i32 s39, 0, 0x18000
	v_add_u32_e32 v152, s39, v146
	s_barrier
	ds_read_b128 v[136:139], v152
	ds_read_b128 v[140:143], v152 offset:1024
	ds_read_b128 v[148:151], v152 offset:2048
	ds_read_b128 v[152:155], v152 offset:3072
	s_add_u32 s26, s26, 0xd0000
	s_addc_u32 s27, s27, 0
	s_mov_b32 m0, s48
	v_lshl_add_u64 v[206:207], s[26:27], 0, v[0:1]
	ds_read_b128 v[156:159], v147 offset:32768
	ds_read_b128 v[160:163], v147 offset:33792
	ds_read_b128 v[164:167], v147 offset:34816
	ds_read_b128 v[168:171], v147 offset:35840
	ds_read_b128 v[172:175], v147 offset:36864
	ds_read_b128 v[184:187], v147 offset:37888
	ds_read_b128 v[188:191], v147 offset:38912
	ds_read_b128 v[202:205], v147 offset:39936
	global_load_lds_dwordx4 v[206:207], off
	v_lshl_add_u64 v[206:207], s[26:27], 0, v[132:133]
	s_mov_b32 m0, s49
	s_nop 0
	global_load_lds_dwordx4 v[206:207], off
	s_waitcnt lgkmcnt(8)
	s_barrier
	s_waitcnt lgkmcnt(0)
	s_setprio 1
	s_waitcnt lgkmcnt(0)
	v_mfma_f32_16x16x32_bf16 v[126:129], v[136:139], v[156:159], v[126:129]
	v_mfma_f32_16x16x32_bf16 v[122:125], v[148:151], v[156:159], v[122:125]
	v_mfma_f32_16x16x32_bf16 v[110:113], v[136:139], v[164:167], v[110:113]
	v_mfma_f32_16x16x32_bf16 v[106:109], v[148:151], v[164:167], v[106:109]
	v_mfma_f32_16x16x32_bf16 v[94:97], v[136:139], v[172:175], v[94:97]
	v_mfma_f32_16x16x32_bf16 v[90:93], v[148:151], v[172:175], v[90:93]
	v_mfma_f32_16x16x32_bf16 v[78:81], v[136:139], v[188:191], v[78:81]
	v_mfma_f32_16x16x32_bf16 v[74:77], v[148:151], v[188:191], v[74:77]
	v_mfma_f32_16x16x32_bf16 v[126:129], v[140:143], v[160:163], v[126:129]
	v_mfma_f32_16x16x32_bf16 v[122:125], v[152:155], v[160:163], v[122:125]
	v_mfma_f32_16x16x32_bf16 v[110:113], v[140:143], v[168:171], v[110:113]
	v_mfma_f32_16x16x32_bf16 v[106:109], v[152:155], v[168:171], v[106:109]
	v_mfma_f32_16x16x32_bf16 v[94:97], v[140:143], v[184:187], v[94:97]
	v_mfma_f32_16x16x32_bf16 v[90:93], v[152:155], v[184:187], v[90:93]
	v_mfma_f32_16x16x32_bf16 v[78:81], v[140:143], v[202:205], v[78:81]
	v_mfma_f32_16x16x32_bf16 v[74:77], v[152:155], v[202:205], v[74:77]
	s_setprio 0
	s_barrier
	s_add_i32 s26, 0, 0x1c000
	s_add_i32 s27, s39, s36
	v_add_u32_e32 v182, s26, v146
	v_lshl_add_u64 v[176:177], v[176:177], 0, s[90:91]
	s_mov_b32 m0, s27
	ds_read_b128 v[206:209], v182
	ds_read_b128 v[210:213], v182 offset:1024
	ds_read_b128 v[214:217], v182 offset:2048
	ds_read_b128 v[218:221], v182 offset:3072
	global_load_lds_dwordx4 v[176:177], off
	v_lshl_add_u64 v[176:177], v[178:179], 0, s[90:91]
	s_add_i32 m0, s27, 0x2000
	s_nop 0
	global_load_lds_dwordx4 v[176:177], off
	s_barrier
	s_waitcnt lgkmcnt(0)
	s_setprio 1
	s_waitcnt lgkmcnt(0)
	v_mfma_f32_16x16x32_bf16 v[118:121], v[206:209], v[156:159], v[118:121]
	v_mfma_f32_16x16x32_bf16 v[114:117], v[214:217], v[156:159], v[114:117]
	v_mfma_f32_16x16x32_bf16 v[102:105], v[206:209], v[164:167], v[102:105]
	v_mfma_f32_16x16x32_bf16 v[98:101], v[214:217], v[164:167], v[98:101]
	v_mfma_f32_16x16x32_bf16 v[86:89], v[206:209], v[172:175], v[86:89]
	v_mfma_f32_16x16x32_bf16 v[82:85], v[214:217], v[172:175], v[82:85]
	v_mfma_f32_16x16x32_bf16 v[70:73], v[206:209], v[188:191], v[70:73]
	v_mfma_f32_16x16x32_bf16 v[66:69], v[214:217], v[188:191], v[66:69]
	v_mfma_f32_16x16x32_bf16 v[118:121], v[210:213], v[160:163], v[118:121]
	v_mfma_f32_16x16x32_bf16 v[114:117], v[218:221], v[160:163], v[114:117]
	v_mfma_f32_16x16x32_bf16 v[102:105], v[210:213], v[168:171], v[102:105]
	v_mfma_f32_16x16x32_bf16 v[98:101], v[218:221], v[168:171], v[98:101]
	v_mfma_f32_16x16x32_bf16 v[86:89], v[210:213], v[184:187], v[86:89]
	v_mfma_f32_16x16x32_bf16 v[82:85], v[218:221], v[184:187], v[82:85]
	v_mfma_f32_16x16x32_bf16 v[70:73], v[210:213], v[202:205], v[70:73]
	v_mfma_f32_16x16x32_bf16 v[66:69], v[218:221], v[202:205], v[66:69]
	s_setprio 0
	s_mov_b32 m0, s54
	v_lshl_add_u64 v[176:177], v[180:181], 0, s[90:91]
	s_barrier
	ds_read_b128 v[156:159], v147 offset:49152
	ds_read_b128 v[160:163], v147 offset:50176
	ds_read_b128 v[164:167], v147 offset:51200
	ds_read_b128 v[168:171], v147 offset:52224
	ds_read_b128 v[172:175], v147 offset:53248
	ds_read_b128 v[184:187], v147 offset:54272
	ds_read_b128 v[188:191], v147 offset:55296
	ds_read_b128 v[202:205], v147 offset:56320
	global_load_lds_dwordx4 v[176:177], off
	v_lshl_add_u64 v[176:177], v[222:223], 0, s[90:91]
	s_mov_b32 m0, s55
	s_nop 0
	global_load_lds_dwordx4 v[176:177], off
	s_barrier
; #define PG8_STAGE(bufoff, gbase, voff) do { _Pragma("unroll") for (int _i = 0; _i < 2; ++_i) \
;         __builtin_amdgcn_global_load_lds((const unsigned*)((const char*)(gbase) + (voff)[_i]), (LAS unsigned*)(lds + (bufoff) + ldsw + _i * 8192), 16, 0, 0); } while (0)
; #define PG8_LDA(dst, b, h) do { _Pragma("unroll") for (int m = 0; m < 4; ++m) _Pragma("unroll") for (int k = 0; k < 2; ++k) dst[m][k] = *(const LAS bf16x8*)(lds + PG8_SA(b, h) + aoff + m * 2048 + k * 1024); } while (0)
; #define PG8_MMA(ai, bj, At, Bt) do { __builtin_amdgcn_s_setprio(1); _Pragma("unroll") for (int m = 0; m < 4; ++m) _Pragma("unroll") for (int n = 0; n < 2; ++n) _Pragma("unroll") for (int k = 0; k < 2; ++k) \
;         acc[ai][bj][m][n] = __builtin_amdgcn_mfma_f32_16x16x32_bf16(Bt[n][k], At[m][k], acc[ai][bj][m][n], 0, 0, 0); __builtin_amdgcn_s_setprio(0); } while (0)
; #define PG8_WAIT_V(n) asm volatile("s_waitcnt vmcnt(" #n ")" ::: "memory")
; #define PG8_WAIT_L(n) asm volatile("s_waitcnt lgkmcnt(" #n ")" ::: "memory")
; #define PG8_BAR __builtin_amdgcn_s_barrier()
; #define PG8_SCHED __builtin_amdgcn_sched_barrier(0)
; template <class Epi, class SchedT>
; DI void gemm_phase(LAS unsigned char* lds, const Gemm g, const SchedT& S, const Epi& E) {
;     ...
;             PG8_LDA(At, 1, 1); PG8_STAGE(PG8_SA(1, 0), a3, voffA);
;             PG8_BAR; PG8_WAIT_L(0); PG8_MMA(1, 0, At, B0); PG8_BAR; PG8_SCHED;
;             PG8_STAGE(PG8_SB(1, 1), b3 + hstepB, voffB);
;             PG8_WAIT_V(6); PG8_BAR; PG8_MMA(1, 1, At, B1); PG8_BAR;
;         }
	s_waitcnt lgkmcnt(0)
	s_setprio 1
	s_waitcnt lgkmcnt(0)
	v_mfma_f32_16x16x32_bf16 v[62:65], v[136:139], v[156:159], v[62:65]
	v_mfma_f32_16x16x32_bf16 v[58:61], v[148:151], v[156:159], v[58:61]
	v_mfma_f32_16x16x32_bf16 v[46:49], v[136:139], v[164:167], v[46:49]
	v_mfma_f32_16x16x32_bf16 v[42:45], v[148:151], v[164:167], v[42:45]
	v_mfma_f32_16x16x32_bf16 v[30:33], v[136:139], v[172:175], v[30:33]
	v_mfma_f32_16x16x32_bf16 v[26:29], v[148:151], v[172:175], v[26:29]
	v_mfma_f32_16x16x32_bf16 v[14:17], v[136:139], v[188:191], v[14:17]
	v_mfma_f32_16x16x32_bf16 v[10:13], v[148:151], v[188:191], v[10:13]
	v_mfma_f32_16x16x32_bf16 v[62:65], v[140:143], v[160:163], v[62:65]
	v_mfma_f32_16x16x32_bf16 v[58:61], v[152:155], v[160:163], v[58:61]
	v_mfma_f32_16x16x32_bf16 v[46:49], v[140:143], v[168:171], v[46:49]
	v_mfma_f32_16x16x32_bf16 v[42:45], v[152:155], v[168:171], v[42:45]
	v_mfma_f32_16x16x32_bf16 v[30:33], v[140:143], v[184:187], v[30:33]
	v_mfma_f32_16x16x32_bf16 v[26:29], v[152:155], v[184:187], v[26:29]
	v_mfma_f32_16x16x32_bf16 v[14:17], v[140:143], v[202:205], v[14:17]
	v_mfma_f32_16x16x32_bf16 v[10:13], v[152:155], v[202:205], v[10:13]
	s_setprio 0
	s_barrier
	s_add_u32 s24, s24, 0x20080
	s_addc_u32 s25, s25, 0
	s_add_i32 s26, s26, s36
	v_lshl_add_u64 v[136:137], s[24:25], 0, v[130:131]
	s_mov_b32 m0, s26
	s_nop 0
	global_load_lds_dwordx4 v[136:137], off
	v_lshl_add_u64 v[136:137], s[24:25], 0, v[134:135]
	s_add_i32 m0, s26, 0x2000
	s_nop 0
	global_load_lds_dwordx4 v[136:137], off
	s_waitcnt vmcnt(6)
	s_barrier
	s_setprio 1
	v_mfma_f32_16x16x32_bf16 v[54:57], v[206:209], v[156:159], v[54:57]
	v_mfma_f32_16x16x32_bf16 v[50:53], v[214:217], v[156:159], v[50:53]
	v_mfma_f32_16x16x32_bf16 v[38:41], v[206:209], v[164:167], v[38:41]
	v_mfma_f32_16x16x32_bf16 v[34:37], v[214:217], v[164:167], v[34:37]
	v_mfma_f32_16x16x32_bf16 v[22:25], v[206:209], v[172:175], v[22:25]
	v_mfma_f32_16x16x32_bf16 v[18:21], v[214:217], v[172:175], v[18:21]
	v_mfma_f32_16x16x32_bf16 v[6:9], v[206:209], v[188:191], v[6:9]
	v_mfma_f32_16x16x32_bf16 v[2:5], v[214:217], v[188:191], v[2:5]
	v_mfma_f32_16x16x32_bf16 v[54:57], v[210:213], v[160:163], v[54:57]
	v_mfma_f32_16x16x32_bf16 v[50:53], v[218:221], v[160:163], v[50:53]
	v_mfma_f32_16x16x32_bf16 v[38:41], v[210:213], v[168:171], v[38:41]
	v_mfma_f32_16x16x32_bf16 v[34:37], v[218:221], v[168:171], v[34:37]
	v_mfma_f32_16x16x32_bf16 v[22:25], v[210:213], v[184:187], v[22:25]
	v_mfma_f32_16x16x32_bf16 v[18:21], v[218:221], v[184:187], v[18:21]
	v_mfma_f32_16x16x32_bf16 v[6:9], v[210:213], v[202:205], v[6:9]
	v_mfma_f32_16x16x32_bf16 v[2:5], v[218:221], v[202:205], v[2:5]
	s_setprio 0
	s_add_i32 s38, s38, 2
	s_add_u32 s0, s0, 0x100
	s_addc_u32 s1, s1, 0
	s_add_u32 s29, s29, 0x100
	s_addc_u32 s33, s33, 0
	s_cmp_gt_u32 s38, 5
	s_barrier
	s_cbranch_scc0 .LBB0_643
; DI u32x4 pk8(f32x4 a, f32x4 b) { u32x4 w; w.x = pk2(a[0], a[1]); w.y = pk2(a[2], a[3]); w.z = pk2(b[0], b[1]); w.w = pk2(b[2], b[3]); return w; }
; DI float row_rstd(const float* ssq, int row, int which) { const f32x4 a = *(const f32x4*)(ssq + (size_t)row * 16 + which * 8), b = *(const f32x4*)(ssq + (size_t)row * 16 + which * 8 + 4);
;     const float s = ((a[0] + a[1]) + (a[2] + a[3])) + ((b[0] + b[1]) + (b[2] + b[3])); return __builtin_amdgcn_rsqf(s * (1.f / 512.f) + EPS); }
;     DI void operator()(AccRef acc, const Unit& u, int wr, int wc, int fr, int fq) const {
;         const int rowb = u.pm * 256 + wr * 64 + fr;
; #pragma unroll
;         for (int ai = 0; ai < 2; ++ai)
; #pragma unroll
;             for (int m = 0; m < 4; ++m) { const int row = rowb + ai * 128 + m * 16; const float rs = row_rstd(ssq, row, 0) * scale;
; #pragma unroll
;                 for (int bj = 0; bj < 2; ++bj) { const int c32 = 256 * u.pn + 128 * bj + 32 * wc; f32x4 v0 = acc[ai][bj][m][0] * rs, v1 = acc[ai][bj][m][1] * rs;
;                     if (((c32 >> 6) % 3) == 2 && row < ML) rope8(v0, v1, row, (c32 >> 5) & 1, fq, fq * 16 + fr, rope);
;                     *(u32x4*)(Q + (size_t)row * 1536 + c32 + 8 * fq) = pk8(v0, v1); } }
	s_mov_b32 s0, s52
	v_mov_b32_e32 v148, v144
	s_mov_b32 s1, s35
	v_mov_b32_e32 v0, v145
	s_lshl_b32 s5, s28, 8
	s_lshl_b32 s1, s1, 6
	s_add_i32 s1, s1, s5
	v_add_u32_e32 v134, s1, v148
	v_ashrrev_i32_e32 v135, 31, v134
	v_lshlrev_b64 v[136:137], 6, v[134:135]
	v_lshl_add_u64 v[140:141], s[12:13], 0, v[136:137]
	v_mov_b32_e32 v170, v140
	v_mov_b32_e32 v171, v141
	global_load_dwordx4 v[136:139], v[140:141], off
	s_nop 0
	global_load_dwordx4 v[140:143], v[140:141], off offset:16
	s_mov_b64 s[98:99], 0x2000
	v_lshl_add_u64 v[172:173], v[170:171], 0, s[98:99]
	global_load_dwordx4 v[202:205], v[170:171], off offset:1024
	global_load_dwordx4 v[206:209], v[170:171], off offset:1040
	global_load_dwordx4 v[210:213], v[170:171], off offset:2048
	global_load_dwordx4 v[214:217], v[170:171], off offset:2064
	global_load_dwordx4 v[218:221], v[170:171], off offset:3072
	global_load_dwordx4 v[222:225], v[170:171], off offset:3088
	global_load_dwordx4 v[226:229], v[172:173], off offset:0
	global_load_dwordx4 v[230:233], v[172:173], off offset:16
	global_load_dwordx4 v[234:237], v[172:173], off offset:1024
	global_load_dwordx4 v[238:241], v[172:173], off offset:1040
	global_load_dwordx4 v[242:245], v[172:173], off offset:2048
	global_load_dwordx4 v[246:249], v[172:173], off offset:2064
	global_load_dwordx4 v[250:253], v[172:173], off offset:3072
	global_load_dwordx4 v[166:169], v[172:173], off offset:3088
	s_lshl_b32 s1, s4, 8
	s_lshl_b32 s4, s0, 5
	s_add_i32 s24, s4, s1
	v_lshlrev_b32_e32 v131, 2, v148
	v_lshlrev_b32_e32 v132, 3, v0
	s_bitcmp0_b32 s0, 0
	v_cmp_gt_i32_e64 s[0:1], 2, v0
	v_lshl_add_u32 v0, v0, 6, v131
	v_xor_b32_e32 v131, 0x80, v0
	s_cselect_b64 vcc, -1, 0
	v_cndmask_b32_e64 v130, 1.0, -1.0, s[0:1]
	s_ashr_i32 s0, s24, 6
	s_mul_hi_i32 s1, s0, 0x55555556
	s_lshr_b32 s19, s1, 31
	s_add_i32 s1, s1, s19
	s_mul_i32 s1, s1, 3
	s_sub_i32 s0, s0, s1
	s_cmp_eq_u32 s0, 2
	v_and_b32_e32 v133, 8, v132
	v_cmp_gt_i32_e64 s[4:5], s72, v134
	s_cselect_b64 s[0:1], -1, 0
	s_and_b64 s[28:29], s[4:5], s[0:1]
	s_waitcnt vmcnt(0)
	v_mov_b32_e32 v150, v136
	v_mov_b32_e32 v151, v140
	v_mov_b32_e32 v140, v137
	v_pk_add_f32 v[136:137], v[150:151], v[140:141]
	v_mov_b32_e32 v140, v138
	v_mov_b32_e32 v141, v142
	v_mov_b32_e32 v142, v139
	v_pk_add_f32 v[138:139], v[140:141], v[142:143]
	s_nop 0
	v_pk_add_f32 v[136:137], v[136:137], v[138:139]
	s_nop 0
	v_add_f32_e32 v0, v136, v137
	v_fmamk_f32 v0, v0, 0x3b000000, v193
	v_rsq_f32_e32 v0, v0
	s_nop 0
	v_mul_f32_e32 v136, 0x3dd53b94, v0
	v_lshrrev_b32_e32 v0, 6, v134
	v_cndmask_b32_e32 v0, v148, v0, vcc
	v_lshlrev_b32_e32 v0, 4, v0
	v_and_b32_e32 v0, 0x3f0, v0
	v_pk_mul_f32 v[140:141], v[128:129], v[136:137] op_sel_hi:[1,0]
	v_pk_mul_f32 v[128:129], v[126:127], v[136:137] op_sel_hi:[1,0]
	v_pk_mul_f32 v[142:143], v[124:125], v[136:137] op_sel_hi:[1,0]
	v_pk_mul_f32 v[138:139], v[122:123], v[136:137] op_sel_hi:[1,0]
	v_lshlrev_b32_e32 v0, 3, v0
	v_lshlrev_b32_e32 v126, 3, v133
	s_and_saveexec_b64 s[26:27], s[28:29]
	s_cbranch_execz .LBB0_646
	v_lshl_add_u64 v[122:123], s[16:17], 0, v[0:1]
	v_mov_b32_e32 v127, v1
	v_lshl_add_u64 v[158:159], v[122:123], 0, v[126:127]
	global_load_dwordx4 v[122:125], v[158:159], off offset:48
	global_load_dwordx4 v[150:153], v[158:159], off offset:16
	global_load_dwordx4 v[154:157], v[158:159], off offset:32
	s_nop 0
	global_load_dwordx4 v[158:161], v[158:159], off
	ds_bpermute_b32 v127, v131, v138
	ds_bpermute_b32 v162, v131, v128
	ds_bpermute_b32 v163, v131, v129
	ds_bpermute_b32 v133, v131, v142
	v_mov_b32_e32 v164, v138
	s_waitcnt lgkmcnt(0)
	v_mul_f32_e32 v165, v130, v127
	ds_bpermute_b32 v127, v131, v139
	v_pk_mul_f32 v[162:163], v[130:131], v[162:163] op_sel_hi:[0,1]
	s_waitcnt vmcnt(1)
	v_mul_f32_e32 v138, v165, v155
	v_pk_fma_f32 v[154:155], v[164:165], v[154:155], v[138:139] op_sel_hi:[1,1,0]
	s_waitcnt vmcnt(0)
	v_mov_b32_e32 v165, v160
	v_mov_b32_e32 v160, v159
	v_mov_b32_e32 v164, v158
	v_pk_mul_f32 v[158:159], v[162:163], v[160:161]
	s_waitcnt lgkmcnt(0)
	v_mul_f32_e32 v161, v130, v127
	v_mov_b32_e32 v160, v139
	v_mul_f32_e32 v138, v139, v156
	v_pk_fma_f32 v[138:139], v[160:161], v[156:157], v[138:139] op_sel_hi:[1,1,0]
	ds_bpermute_b32 v127, v131, v140
	v_mul_f32_e32 v157, v130, v133
	v_mov_b32_e32 v156, v142
	v_mul_f32_e32 v138, v157, v123
	v_pk_fma_f32 v[122:123], v[156:157], v[122:123], v[138:139] op_sel_hi:[1,1,0]
	ds_bpermute_b32 v123, v131, v141
	s_waitcnt lgkmcnt(1)
	v_mul_f32_e32 v127, v130, v127
	v_mul_f32_e32 v140, v140, v150
	v_mul_f32_e32 v150, v127, v151
	ds_bpermute_b32 v127, v131, v143
	s_waitcnt lgkmcnt(1)
	v_mul_f32_e32 v157, v130, v123
	v_mov_b32_e32 v156, v141
	v_pk_mul_f32 v[152:153], v[156:157], v[152:153]
	v_pk_fma_f32 v[128:129], v[128:129], v[164:165], v[158:159]
	v_mov_b32_e32 v141, v152
	v_mov_b32_e32 v151, v153
	v_pk_add_f32 v[140:141], v[140:141], v[150:151]
	s_waitcnt lgkmcnt(0)
	v_mul_f32_e32 v151, v130, v127
	v_mov_b32_e32 v150, v143
	v_mul_f32_e32 v138, v151, v125
	v_pk_fma_f32 v[124:125], v[150:151], v[124:125], v[138:139] op_sel_hi:[1,1,0]
	v_mov_b32_e32 v138, v154
	v_mov_b32_e32 v142, v122
	v_mov_b32_e32 v143, v124

; DI float shx(float v, int m, int lane) { return __builtin_bit_cast(float, __builtin_amdgcn_ds_bpermute((lane ^ m) << 2, __builtin_bit_cast(int, v))); }
; DI u32x4 pk8(f32x4 a, f32x4 b) { u32x4 w; w.x = pk2(a[0], a[1]); w.y = pk2(a[2], a[3]); w.z = pk2(b[0], b[1]); w.w = pk2(b[2], b[3]); return w; }
; DI void rope8(f32x4& v0, f32x4& v1, int row, int axis, int fq, int lane, const f32x2* rope) {
;     const int l = row & 4095, pos = axis ? (l & 63) : (l >> 6);
;     const f32x2* t = rope + pos * 16 + 8 * (fq & 1);
;     const float sgn = (fq < 2) ? -1.f : 1.f;
; #pragma unroll
;     for (int j = 0; j < 4; ++j) {
;         const float p0 = shx(v0[j], 32, lane), p1 = shx(v1[j], 32, lane);
;         const f32x2 c0 = t[j], c1 = t[4 + j];
;         v0[j] = v0[j] * c0.x + sgn * p0 * c0.y; v1[j] = v1[j] * c1.x + sgn * p1 * c1.y;
;     }
; }
; DI float row_rstd(const float* ssq, int row, int which) { const f32x4 a = *(const f32x4*)(ssq + (size_t)row * 16 + which * 8), b = *(const f32x4*)(ssq + (size_t)row * 16 + which * 8 + 4);
;     const float s = ((a[0] + a[1]) + (a[2] + a[3])) + ((b[0] + b[1]) + (b[2] + b[3])); return __builtin_amdgcn_rsqf(s * (1.f / 512.f) + EPS); }
;     DI void operator()(AccRef acc, const Unit& u, int wr, int wc, int fr, int fq) const {
;     ...
;             for (int m = 0; m < 4; ++m) { const int row = rowb + ai * 128 + m * 16; const float rs = row_rstd(ssq, row, 0) * scale;
; #pragma unroll
;                 for (int bj = 0; bj < 2; ++bj) { const int c32 = 256 * u.pn + 128 * bj + 32 * wc; f32x4 v0 = acc[ai][bj][m][0] * rs, v1 = acc[ai][bj][m][1] * rs;
;                     if (((c32 >> 6) % 3) == 2 && row < ML) rope8(v0, v1, row, (c32 >> 5) & 1, fq, fq * 16 + fr, rope);
;                     *(u32x4*)(Q + (size_t)row * 1536 + c32 + 8 * fq) = pk8(v0, v1); } }
.LBB0_648:
	s_or_b64 exec, exec, s[4:5]
	v_cvt_pk_bf16_f32 v114, v118, v119
	v_cvt_pk_bf16_f32 v115, v120, v121
	v_cvt_pk_bf16_f32 v116, v124, v125
	v_cvt_pk_bf16_f32 v117, v128, v129
	global_store_dwordx4 v[122:123], v[114:117], off offset:256
	v_cmp_gt_i32_e64 s[4:5], s92, v134
	s_and_b64 s[38:39], s[4:5], s[0:1]
	v_add_u32_e32 v114, 16, v134
	v_ashrrev_i32_e32 v115, 31, v114
	v_lshlrev_b64 v[116:117], 6, v[114:115]
	v_lshl_add_u64 v[120:121], s[12:13], 0, v[116:117]
	s_nop 0
	v_mov_b32_e32 v116, v202
	v_mov_b32_e32 v117, v203
	v_mov_b32_e32 v118, v204
	v_mov_b32_e32 v119, v205
	v_mov_b32_e32 v120, v206
	v_mov_b32_e32 v121, v207
	v_mov_b32_e32 v122, v208
	v_mov_b32_e32 v123, v209
	v_mov_b32_e32 v124, v116
	v_mov_b32_e32 v125, v120
	v_mov_b32_e32 v120, v117
	v_pk_add_f32 v[116:117], v[124:125], v[120:121]
	v_mov_b32_e32 v120, v118
	v_mov_b32_e32 v121, v122
	v_mov_b32_e32 v122, v119
	v_pk_add_f32 v[118:119], v[120:121], v[122:123]
	s_nop 0
	v_pk_add_f32 v[116:117], v[116:117], v[118:119]
	s_nop 0
	v_add_f32_e32 v0, v116, v117
	v_fmamk_f32 v0, v0, 0x3b000000, v193
	v_rsq_f32_e32 v0, v0
	s_nop 0
	v_mul_f32_e32 v116, 0x3dd53b94, v0
	v_lshrrev_b32_e32 v0, 6, v114
	v_cndmask_b32_e32 v0, v114, v0, vcc
	v_lshlrev_b32_e32 v0, 4, v0
	v_and_b32_e32 v0, 0x3f0, v0
	v_pk_mul_f32 v[118:119], v[112:113], v[116:117] op_sel_hi:[1,0]
	v_pk_mul_f32 v[110:111], v[110:111], v[116:117] op_sel_hi:[1,0]
	v_pk_mul_f32 v[120:121], v[108:109], v[116:117] op_sel_hi:[1,0]
	v_pk_mul_f32 v[112:113], v[106:107], v[116:117] op_sel_hi:[1,0]
	v_lshlrev_b32_e32 v0, 3, v0
	s_and_saveexec_b64 s[28:29], s[38:39]
	s_cbranch_execz .LBB0_650
	v_lshl_add_u64 v[106:107], s[16:17], 0, v[0:1]
	v_mov_b32_e32 v127, v1
	v_lshl_add_u64 v[128:129], v[106:107], 0, v[126:127]
	global_load_dwordx4 v[106:109], v[128:129], off offset:48
	global_load_dwordx4 v[122:125], v[128:129], off offset:16
	global_load_dwordx4 v[136:139], v[128:129], off offset:32
	global_load_dwordx4 v[140:143], v[128:129], off
	ds_bpermute_b32 v115, v131, v112
	ds_bpermute_b32 v150, v131, v110
	v_mov_b32_e32 v128, v112
	ds_bpermute_b32 v151, v131, v111
	s_waitcnt lgkmcnt(0)
	v_mul_f32_e32 v129, v130, v115
	ds_bpermute_b32 v115, v131, v120
	v_pk_mul_f32 v[150:151], v[130:131], v[150:151] op_sel_hi:[0,1]
	s_waitcnt vmcnt(1)
	v_mul_f32_e32 v112, v129, v137
	v_pk_fma_f32 v[128:129], v[128:129], v[136:137], v[112:113] op_sel_hi:[1,1,0]
	ds_bpermute_b32 v112, v131, v113
	s_waitcnt vmcnt(0)
	v_mov_b32_e32 v137, v142
	v_mov_b32_e32 v142, v141
	v_mov_b32_e32 v136, v140
	v_pk_mul_f32 v[140:141], v[150:151], v[142:143]
	s_waitcnt lgkmcnt(0)
	v_mul_f32_e32 v143, v130, v112
	v_mov_b32_e32 v142, v113
	v_mul_f32_e32 v112, v113, v138
	v_pk_fma_f32 v[112:113], v[142:143], v[138:139], v[112:113] op_sel_hi:[1,1,0]
	ds_bpermute_b32 v112, v131, v118
	v_mul_f32_e32 v139, v130, v115
	v_mul_f32_e32 v118, v118, v122
	v_mov_b32_e32 v138, v120
	v_pk_fma_f32 v[110:111], v[110:111], v[136:137], v[140:141]
	s_waitcnt lgkmcnt(0)
	v_mul_f32_e32 v112, v130, v112
	v_mul_f32_e32 v122, v112, v123
	v_mul_f32_e32 v112, v139, v107
	v_pk_fma_f32 v[106:107], v[138:139], v[106:107], v[112:113] op_sel_hi:[1,1,0]
	ds_bpermute_b32 v107, v131, v119
	ds_bpermute_b32 v112, v131, v121
	v_mov_b32_e32 v138, v119
	v_mov_b32_e32 v120, v106
	s_waitcnt lgkmcnt(1)
	v_mul_f32_e32 v139, v130, v107
	v_pk_mul_f32 v[124:125], v[138:139], v[124:125]
	s_nop 0
	v_mov_b32_e32 v119, v124
	v_mov_b32_e32 v123, v125
	v_pk_add_f32 v[118:119], v[118:119], v[122:123]
	s_waitcnt lgkmcnt(0)
	v_mul_f32_e32 v123, v130, v112
	v_mov_b32_e32 v122, v121
	v_mul_f32_e32 v112, v123, v109
	v_pk_fma_f32 v[108:109], v[122:123], v[108:109], v[112:113] op_sel_hi:[1,1,0]
	v_mov_b32_e32 v112, v128
	v_mov_b32_e32 v121, v108

; DI float shx(float v, int m, int lane) { return __builtin_bit_cast(float, __builtin_amdgcn_ds_bpermute((lane ^ m) << 2, __builtin_bit_cast(int, v))); }
; DI u32x4 pk8(f32x4 a, f32x4 b) { u32x4 w; w.x = pk2(a[0], a[1]); w.y = pk2(a[2], a[3]); w.z = pk2(b[0], b[1]); w.w = pk2(b[2], b[3]); return w; }
; DI void rope8(f32x4& v0, f32x4& v1, int row, int axis, int fq, int lane, const f32x2* rope) {
;     const int l = row & 4095, pos = axis ? (l & 63) : (l >> 6);
;     const f32x2* t = rope + pos * 16 + 8 * (fq & 1);
;     const float sgn = (fq < 2) ? -1.f : 1.f;
; #pragma unroll
;     for (int j = 0; j < 4; ++j) {
;         const float p0 = shx(v0[j], 32, lane), p1 = shx(v1[j], 32, lane);
;         const f32x2 c0 = t[j], c1 = t[4 + j];
;         v0[j] = v0[j] * c0.x + sgn * p0 * c0.y; v1[j] = v1[j] * c1.x + sgn * p1 * c1.y;
;     }
; }
; DI float row_rstd(const float* ssq, int row, int which) { const f32x4 a = *(const f32x4*)(ssq + (size_t)row * 16 + which * 8), b = *(const f32x4*)(ssq + (size_t)row * 16 + which * 8 + 4);
;     const float s = ((a[0] + a[1]) + (a[2] + a[3])) + ((b[0] + b[1]) + (b[2] + b[3])); return __builtin_amdgcn_rsqf(s * (1.f / 512.f) + EPS); }
;     DI void operator()(AccRef acc, const Unit& u, int wr, int wc, int fr, int fq) const {
;     ...
;             for (int m = 0; m < 4; ++m) { const int row = rowb + ai * 128 + m * 16; const float rs = row_rstd(ssq, row, 0) * scale;
; #pragma unroll
;                 for (int bj = 0; bj < 2; ++bj) { const int c32 = 256 * u.pn + 128 * bj + 32 * wc; f32x4 v0 = acc[ai][bj][m][0] * rs, v1 = acc[ai][bj][m][1] * rs;
;                     if (((c32 >> 6) % 3) == 2 && row < ML) rope8(v0, v1, row, (c32 >> 5) & 1, fq, fq * 16 + fr, rope);
;                     *(u32x4*)(Q + (size_t)row * 1536 + c32 + 8 * fq) = pk8(v0, v1); } }
.LBB0_652:
	s_or_b64 exec, exec, s[4:5]
	v_cvt_pk_bf16_f32 v98, v102, v103
	v_cvt_pk_bf16_f32 v99, v104, v105
	v_cvt_pk_bf16_f32 v100, v108, v109
	v_cvt_pk_bf16_f32 v101, v110, v111
	global_store_dwordx4 v[106:107], v[98:101], off offset:256
	v_cmp_gt_i32_e64 s[4:5], s93, v134
	s_and_b64 s[38:39], s[4:5], s[0:1]
	v_add_u32_e32 v98, 32, v134
	v_ashrrev_i32_e32 v99, 31, v98
	v_lshlrev_b64 v[100:101], 6, v[98:99]
	v_lshl_add_u64 v[104:105], s[12:13], 0, v[100:101]
	s_nop 0
	v_mov_b32_e32 v100, v210
	v_mov_b32_e32 v101, v211
	v_mov_b32_e32 v102, v212
	v_mov_b32_e32 v103, v213
	v_mov_b32_e32 v104, v214
	v_mov_b32_e32 v105, v215
	v_mov_b32_e32 v106, v216
	v_mov_b32_e32 v107, v217
	v_mov_b32_e32 v108, v100
	v_mov_b32_e32 v109, v104
	v_mov_b32_e32 v104, v101
	v_pk_add_f32 v[100:101], v[108:109], v[104:105]
	v_mov_b32_e32 v104, v102
	v_mov_b32_e32 v105, v106
	v_mov_b32_e32 v106, v103
	v_pk_add_f32 v[102:103], v[104:105], v[106:107]
	s_nop 0
	v_pk_add_f32 v[100:101], v[100:101], v[102:103]
	s_nop 0
	v_add_f32_e32 v0, v100, v101
	v_fmamk_f32 v0, v0, 0x3b000000, v193
	v_rsq_f32_e32 v0, v0
	s_nop 0
	v_mul_f32_e32 v100, 0x3dd53b94, v0
	v_lshrrev_b32_e32 v0, 6, v98
	v_cndmask_b32_e32 v0, v98, v0, vcc
	v_lshlrev_b32_e32 v0, 4, v0
	v_and_b32_e32 v0, 0x3f0, v0
	v_pk_mul_f32 v[102:103], v[96:97], v[100:101] op_sel_hi:[1,0]
	v_pk_mul_f32 v[94:95], v[94:95], v[100:101] op_sel_hi:[1,0]
	v_pk_mul_f32 v[104:105], v[92:93], v[100:101] op_sel_hi:[1,0]
	v_pk_mul_f32 v[96:97], v[90:91], v[100:101] op_sel_hi:[1,0]
	v_lshlrev_b32_e32 v0, 3, v0
	s_and_saveexec_b64 s[28:29], s[38:39]
	s_cbranch_execz .LBB0_654
	v_lshl_add_u64 v[90:91], s[16:17], 0, v[0:1]
	v_mov_b32_e32 v127, v1
	v_lshl_add_u64 v[114:115], v[90:91], 0, v[126:127]
	global_load_dwordx4 v[90:93], v[114:115], off offset:48
	global_load_dwordx4 v[106:109], v[114:115], off offset:16
	global_load_dwordx4 v[110:113], v[114:115], off offset:32
	s_nop 0
	global_load_dwordx4 v[114:117], v[114:115], off
	ds_bpermute_b32 v99, v131, v96
	ds_bpermute_b32 v118, v131, v94
	v_mov_b32_e32 v120, v96
	ds_bpermute_b32 v119, v131, v95
	s_waitcnt lgkmcnt(0)
	v_mul_f32_e32 v121, v130, v99
	ds_bpermute_b32 v99, v131, v104
	v_pk_mul_f32 v[118:119], v[130:131], v[118:119] op_sel_hi:[0,1]
	s_waitcnt vmcnt(1)
	v_mul_f32_e32 v96, v121, v111
	v_pk_fma_f32 v[110:111], v[120:121], v[110:111], v[96:97] op_sel_hi:[1,1,0]
	ds_bpermute_b32 v96, v131, v97
	s_waitcnt vmcnt(0)
	v_mov_b32_e32 v121, v116
	v_mov_b32_e32 v116, v115
	v_mov_b32_e32 v120, v114
	v_pk_mul_f32 v[114:115], v[118:119], v[116:117]
	s_waitcnt lgkmcnt(0)
	v_mul_f32_e32 v117, v130, v96
	v_mov_b32_e32 v116, v97
	v_mul_f32_e32 v96, v97, v112
	v_pk_fma_f32 v[96:97], v[116:117], v[112:113], v[96:97] op_sel_hi:[1,1,0]
	ds_bpermute_b32 v96, v131, v102
	v_mul_f32_e32 v113, v130, v99
	v_mul_f32_e32 v102, v102, v106
	v_mov_b32_e32 v112, v104
	v_pk_fma_f32 v[94:95], v[94:95], v[120:121], v[114:115]
	s_waitcnt lgkmcnt(0)
	v_mul_f32_e32 v96, v130, v96
	v_mul_f32_e32 v106, v96, v107
	v_mul_f32_e32 v96, v113, v91
	v_pk_fma_f32 v[90:91], v[112:113], v[90:91], v[96:97] op_sel_hi:[1,1,0]
	ds_bpermute_b32 v91, v131, v103
	ds_bpermute_b32 v96, v131, v105
	v_mov_b32_e32 v112, v103
	v_mov_b32_e32 v104, v90
	s_waitcnt lgkmcnt(1)
	v_mul_f32_e32 v113, v130, v91
	v_pk_mul_f32 v[108:109], v[112:113], v[108:109]
	s_nop 0
	v_mov_b32_e32 v103, v108
	v_mov_b32_e32 v107, v109
	v_pk_add_f32 v[102:103], v[102:103], v[106:107]
	s_waitcnt lgkmcnt(0)
	v_mul_f32_e32 v107, v130, v96
	v_mov_b32_e32 v106, v105
	v_mul_f32_e32 v96, v107, v93
	v_pk_fma_f32 v[92:93], v[106:107], v[92:93], v[96:97] op_sel_hi:[1,1,0]
	v_mov_b32_e32 v96, v110
	v_mov_b32_e32 v105, v92

; DI float shx(float v, int m, int lane) { return __builtin_bit_cast(float, __builtin_amdgcn_ds_bpermute((lane ^ m) << 2, __builtin_bit_cast(int, v))); }
; DI u32x4 pk8(f32x4 a, f32x4 b) { u32x4 w; w.x = pk2(a[0], a[1]); w.y = pk2(a[2], a[3]); w.z = pk2(b[0], b[1]); w.w = pk2(b[2], b[3]); return w; }
; DI void rope8(f32x4& v0, f32x4& v1, int row, int axis, int fq, int lane, const f32x2* rope) {
;     const int l = row & 4095, pos = axis ? (l & 63) : (l >> 6);
;     const f32x2* t = rope + pos * 16 + 8 * (fq & 1);
;     const float sgn = (fq < 2) ? -1.f : 1.f;
; #pragma unroll
;     for (int j = 0; j < 4; ++j) {
;         const float p0 = shx(v0[j], 32, lane), p1 = shx(v1[j], 32, lane);
;         const f32x2 c0 = t[j], c1 = t[4 + j];
;         v0[j] = v0[j] * c0.x + sgn * p0 * c0.y; v1[j] = v1[j] * c1.x + sgn * p1 * c1.y;
;     }
; }
; DI float row_rstd(const float* ssq, int row, int which) { const f32x4 a = *(const f32x4*)(ssq + (size_t)row * 16 + which * 8), b = *(const f32x4*)(ssq + (size_t)row * 16 + which * 8 + 4);
;     const float s = ((a[0] + a[1]) + (a[2] + a[3])) + ((b[0] + b[1]) + (b[2] + b[3])); return __builtin_amdgcn_rsqf(s * (1.f / 512.f) + EPS); }
;     DI void operator()(AccRef acc, const Unit& u, int wr, int wc, int fr, int fq) const {
;     ...
;             for (int m = 0; m < 4; ++m) { const int row = rowb + ai * 128 + m * 16; const float rs = row_rstd(ssq, row, 0) * scale;
; #pragma unroll
;                 for (int bj = 0; bj < 2; ++bj) { const int c32 = 256 * u.pn + 128 * bj + 32 * wc; f32x4 v0 = acc[ai][bj][m][0] * rs, v1 = acc[ai][bj][m][1] * rs;
;                     if (((c32 >> 6) % 3) == 2 && row < ML) rope8(v0, v1, row, (c32 >> 5) & 1, fq, fq * 16 + fr, rope);
;                     *(u32x4*)(Q + (size_t)row * 1536 + c32 + 8 * fq) = pk8(v0, v1); } }
.LBB0_656:
	s_or_b64 exec, exec, s[4:5]
	v_cvt_pk_bf16_f32 v82, v86, v87
	v_cvt_pk_bf16_f32 v83, v88, v89
	v_cvt_pk_bf16_f32 v84, v92, v93
	v_cvt_pk_bf16_f32 v85, v94, v95
	global_store_dwordx4 v[90:91], v[82:85], off offset:256
	v_cmp_gt_i32_e64 s[4:5], s94, v134
	s_and_b64 s[38:39], s[4:5], s[0:1]
	v_add_u32_e32 v82, 48, v134
	v_ashrrev_i32_e32 v83, 31, v82
	v_lshlrev_b64 v[84:85], 6, v[82:83]
	v_lshl_add_u64 v[88:89], s[12:13], 0, v[84:85]
	s_nop 0
	v_mov_b32_e32 v84, v218
	v_mov_b32_e32 v85, v219
	v_mov_b32_e32 v86, v220
	v_mov_b32_e32 v87, v221
	v_mov_b32_e32 v88, v222
	v_mov_b32_e32 v89, v223
	v_mov_b32_e32 v90, v224
	v_mov_b32_e32 v91, v225
	v_mov_b32_e32 v92, v84
	v_mov_b32_e32 v93, v88
	v_mov_b32_e32 v88, v85
	v_pk_add_f32 v[84:85], v[92:93], v[88:89]
	v_mov_b32_e32 v88, v86
	v_mov_b32_e32 v89, v90
	v_mov_b32_e32 v90, v87
	v_pk_add_f32 v[86:87], v[88:89], v[90:91]
	s_nop 0
	v_pk_add_f32 v[84:85], v[84:85], v[86:87]
	s_nop 0
	v_add_f32_e32 v0, v84, v85
	v_fmamk_f32 v0, v0, 0x3b000000, v193
	v_rsq_f32_e32 v0, v0
	s_nop 0
	v_mul_f32_e32 v84, 0x3dd53b94, v0
	v_lshrrev_b32_e32 v0, 6, v82
	v_cndmask_b32_e32 v0, v82, v0, vcc
	v_lshlrev_b32_e32 v0, 4, v0
	v_and_b32_e32 v0, 0x3f0, v0
	v_pk_mul_f32 v[86:87], v[80:81], v[84:85] op_sel_hi:[1,0]
	v_pk_mul_f32 v[78:79], v[78:79], v[84:85] op_sel_hi:[1,0]
	v_pk_mul_f32 v[88:89], v[76:77], v[84:85] op_sel_hi:[1,0]
	v_pk_mul_f32 v[80:81], v[74:75], v[84:85] op_sel_hi:[1,0]
	v_lshlrev_b32_e32 v0, 3, v0
	s_and_saveexec_b64 s[28:29], s[38:39]
	s_cbranch_execz .LBB0_658
	v_lshl_add_u64 v[74:75], s[16:17], 0, v[0:1]
	v_mov_b32_e32 v127, v1
	v_lshl_add_u64 v[98:99], v[74:75], 0, v[126:127]
	global_load_dwordx4 v[74:77], v[98:99], off offset:48
	global_load_dwordx4 v[90:93], v[98:99], off offset:16
	global_load_dwordx4 v[94:97], v[98:99], off offset:32
	s_nop 0
	global_load_dwordx4 v[98:101], v[98:99], off
	ds_bpermute_b32 v83, v131, v80
	ds_bpermute_b32 v102, v131, v78
	v_mov_b32_e32 v104, v80
	ds_bpermute_b32 v103, v131, v79
	s_waitcnt lgkmcnt(0)
	v_mul_f32_e32 v105, v130, v83
	ds_bpermute_b32 v83, v131, v88
	v_pk_mul_f32 v[102:103], v[130:131], v[102:103] op_sel_hi:[0,1]
	s_waitcnt vmcnt(1)
	v_mul_f32_e32 v80, v105, v95
	v_pk_fma_f32 v[94:95], v[104:105], v[94:95], v[80:81] op_sel_hi:[1,1,0]
	ds_bpermute_b32 v80, v131, v81
	s_waitcnt vmcnt(0)
	v_mov_b32_e32 v105, v100
	v_mov_b32_e32 v100, v99
	v_mov_b32_e32 v104, v98
	v_pk_mul_f32 v[98:99], v[102:103], v[100:101]
	s_waitcnt lgkmcnt(0)
	v_mul_f32_e32 v101, v130, v80
	v_mov_b32_e32 v100, v81
	v_mul_f32_e32 v80, v81, v96
	v_pk_fma_f32 v[80:81], v[100:101], v[96:97], v[80:81] op_sel_hi:[1,1,0]
	ds_bpermute_b32 v80, v131, v86
	v_mul_f32_e32 v97, v130, v83
	v_mul_f32_e32 v86, v86, v90
	v_mov_b32_e32 v96, v88
	v_pk_fma_f32 v[78:79], v[78:79], v[104:105], v[98:99]
	s_waitcnt lgkmcnt(0)
	v_mul_f32_e32 v80, v130, v80
	v_mul_f32_e32 v90, v80, v91
	v_mul_f32_e32 v80, v97, v75
	v_pk_fma_f32 v[74:75], v[96:97], v[74:75], v[80:81] op_sel_hi:[1,1,0]
	ds_bpermute_b32 v75, v131, v87
	ds_bpermute_b32 v80, v131, v89
	v_mov_b32_e32 v96, v87
	v_mov_b32_e32 v88, v74
	s_waitcnt lgkmcnt(1)
	v_mul_f32_e32 v97, v130, v75
	v_pk_mul_f32 v[92:93], v[96:97], v[92:93]
	s_nop 0
	v_mov_b32_e32 v87, v92
	v_mov_b32_e32 v91, v93
	v_pk_add_f32 v[86:87], v[86:87], v[90:91]
	s_waitcnt lgkmcnt(0)
	v_mul_f32_e32 v91, v130, v80
	v_mov_b32_e32 v90, v89
	v_mul_f32_e32 v80, v91, v77
	v_pk_fma_f32 v[76:77], v[90:91], v[76:77], v[80:81] op_sel_hi:[1,1,0]
	v_mov_b32_e32 v80, v94
	v_mov_b32_e32 v89, v76

; DI float shx(float v, int m, int lane) { return __builtin_bit_cast(float, __builtin_amdgcn_ds_bpermute((lane ^ m) << 2, __builtin_bit_cast(int, v))); }
; DI u32x4 pk8(f32x4 a, f32x4 b) { u32x4 w; w.x = pk2(a[0], a[1]); w.y = pk2(a[2], a[3]); w.z = pk2(b[0], b[1]); w.w = pk2(b[2], b[3]); return w; }
; DI void rope8(f32x4& v0, f32x4& v1, int row, int axis, int fq, int lane, const f32x2* rope) {
;     const int l = row & 4095, pos = axis ? (l & 63) : (l >> 6);
;     const f32x2* t = rope + pos * 16 + 8 * (fq & 1);
;     const float sgn = (fq < 2) ? -1.f : 1.f;
; #pragma unroll
;     for (int j = 0; j < 4; ++j) {
;         const float p0 = shx(v0[j], 32, lane), p1 = shx(v1[j], 32, lane);
;         const f32x2 c0 = t[j], c1 = t[4 + j];
;         v0[j] = v0[j] * c0.x + sgn * p0 * c0.y; v1[j] = v1[j] * c1.x + sgn * p1 * c1.y;
;     }
; }
; DI float row_rstd(const float* ssq, int row, int which) { const f32x4 a = *(const f32x4*)(ssq + (size_t)row * 16 + which * 8), b = *(const f32x4*)(ssq + (size_t)row * 16 + which * 8 + 4);
;     const float s = ((a[0] + a[1]) + (a[2] + a[3])) + ((b[0] + b[1]) + (b[2] + b[3])); return __builtin_amdgcn_rsqf(s * (1.f / 512.f) + EPS); }
;     DI void operator()(AccRef acc, const Unit& u, int wr, int wc, int fr, int fq) const {
;     ...
;             for (int m = 0; m < 4; ++m) { const int row = rowb + ai * 128 + m * 16; const float rs = row_rstd(ssq, row, 0) * scale;
; #pragma unroll
;                 for (int bj = 0; bj < 2; ++bj) { const int c32 = 256 * u.pn + 128 * bj + 32 * wc; f32x4 v0 = acc[ai][bj][m][0] * rs, v1 = acc[ai][bj][m][1] * rs;
;                     if (((c32 >> 6) % 3) == 2 && row < ML) rope8(v0, v1, row, (c32 >> 5) & 1, fq, fq * 16 + fr, rope);
;                     *(u32x4*)(Q + (size_t)row * 1536 + c32 + 8 * fq) = pk8(v0, v1); } }
.LBB0_660:
	s_or_b64 exec, exec, s[4:5]
	v_cvt_pk_bf16_f32 v66, v70, v71
	v_cvt_pk_bf16_f32 v67, v72, v73
	v_cvt_pk_bf16_f32 v68, v76, v77
	v_cvt_pk_bf16_f32 v69, v78, v79
	global_store_dwordx4 v[74:75], v[66:69], off offset:256
	v_cmp_gt_i32_e64 s[4:5], s50, v134
	s_and_b64 s[38:39], s[4:5], s[0:1]
	v_add_u32_e32 v66, 0x80, v134
	v_ashrrev_i32_e32 v67, 31, v66
	v_lshlrev_b64 v[68:69], 6, v[66:67]
	v_lshl_add_u64 v[72:73], s[12:13], 0, v[68:69]
	s_nop 0
	v_mov_b32_e32 v68, v226
	v_mov_b32_e32 v69, v227
	v_mov_b32_e32 v70, v228
	v_mov_b32_e32 v71, v229
	v_mov_b32_e32 v72, v230
	v_mov_b32_e32 v73, v231
	v_mov_b32_e32 v74, v232
	v_mov_b32_e32 v75, v233
	v_mov_b32_e32 v76, v68
	v_mov_b32_e32 v77, v72
	v_mov_b32_e32 v72, v69
	v_pk_add_f32 v[68:69], v[76:77], v[72:73]
	v_mov_b32_e32 v72, v70
	v_mov_b32_e32 v73, v74
	v_mov_b32_e32 v74, v71
	v_pk_add_f32 v[70:71], v[72:73], v[74:75]
	s_nop 0
	v_pk_add_f32 v[68:69], v[68:69], v[70:71]
	s_nop 0
	v_add_f32_e32 v0, v68, v69
	v_fmamk_f32 v0, v0, 0x3b000000, v193
	v_rsq_f32_e32 v0, v0
	s_nop 0
	v_mul_f32_e32 v68, 0x3dd53b94, v0
	v_lshrrev_b32_e32 v0, 6, v66
	v_cndmask_b32_e32 v0, v148, v0, vcc
	v_lshlrev_b32_e32 v0, 4, v0
	v_and_b32_e32 v0, 0x3f0, v0
	v_pk_mul_f32 v[70:71], v[64:65], v[68:69] op_sel_hi:[1,0]
	v_pk_mul_f32 v[62:63], v[62:63], v[68:69] op_sel_hi:[1,0]
	v_pk_mul_f32 v[72:73], v[60:61], v[68:69] op_sel_hi:[1,0]
	v_pk_mul_f32 v[64:65], v[58:59], v[68:69] op_sel_hi:[1,0]
	v_lshlrev_b32_e32 v0, 3, v0
	s_and_saveexec_b64 s[28:29], s[38:39]
	s_cbranch_execz .LBB0_662
	v_lshl_add_u64 v[58:59], s[16:17], 0, v[0:1]
	v_mov_b32_e32 v127, v1
	v_lshl_add_u64 v[82:83], v[58:59], 0, v[126:127]
	global_load_dwordx4 v[58:61], v[82:83], off offset:48
	global_load_dwordx4 v[74:77], v[82:83], off offset:16
	global_load_dwordx4 v[78:81], v[82:83], off offset:32
	s_nop 0
	global_load_dwordx4 v[82:85], v[82:83], off
	ds_bpermute_b32 v67, v131, v64
	ds_bpermute_b32 v86, v131, v62
	v_mov_b32_e32 v88, v64
	ds_bpermute_b32 v87, v131, v63
	s_waitcnt lgkmcnt(0)
	v_mul_f32_e32 v89, v130, v67
	ds_bpermute_b32 v67, v131, v72
	v_pk_mul_f32 v[86:87], v[130:131], v[86:87] op_sel_hi:[0,1]
	s_waitcnt vmcnt(1)
	v_mul_f32_e32 v64, v89, v79
	v_pk_fma_f32 v[78:79], v[88:89], v[78:79], v[64:65] op_sel_hi:[1,1,0]
	ds_bpermute_b32 v64, v131, v65
	s_waitcnt vmcnt(0)
	v_mov_b32_e32 v89, v84
	v_mov_b32_e32 v84, v83
	v_mov_b32_e32 v88, v82
	v_pk_mul_f32 v[82:83], v[86:87], v[84:85]
	s_waitcnt lgkmcnt(0)
	v_mul_f32_e32 v85, v130, v64
	v_mov_b32_e32 v84, v65
	v_mul_f32_e32 v64, v65, v80
	v_pk_fma_f32 v[64:65], v[84:85], v[80:81], v[64:65] op_sel_hi:[1,1,0]
	ds_bpermute_b32 v64, v131, v70
	v_mul_f32_e32 v81, v130, v67
	v_mul_f32_e32 v70, v70, v74
	v_mov_b32_e32 v80, v72
	v_pk_fma_f32 v[62:63], v[62:63], v[88:89], v[82:83]
	s_waitcnt lgkmcnt(0)
	v_mul_f32_e32 v64, v130, v64
	v_mul_f32_e32 v74, v64, v75
	v_mul_f32_e32 v64, v81, v59
	v_pk_fma_f32 v[58:59], v[80:81], v[58:59], v[64:65] op_sel_hi:[1,1,0]
	ds_bpermute_b32 v59, v131, v71
	ds_bpermute_b32 v64, v131, v73
	v_mov_b32_e32 v80, v71
	v_mov_b32_e32 v72, v58
	s_waitcnt lgkmcnt(1)
	v_mul_f32_e32 v81, v130, v59
	v_pk_mul_f32 v[76:77], v[80:81], v[76:77]
	s_nop 0
	v_mov_b32_e32 v71, v76
	v_mov_b32_e32 v75, v77
	v_pk_add_f32 v[70:71], v[70:71], v[74:75]
	s_waitcnt lgkmcnt(0)
	v_mul_f32_e32 v75, v130, v64
	v_mov_b32_e32 v74, v73
	v_mul_f32_e32 v64, v75, v61
	v_pk_fma_f32 v[60:61], v[74:75], v[60:61], v[64:65] op_sel_hi:[1,1,0]
	v_mov_b32_e32 v64, v78
	v_mov_b32_e32 v73, v60

; DI float shx(float v, int m, int lane) { return __builtin_bit_cast(float, __builtin_amdgcn_ds_bpermute((lane ^ m) << 2, __builtin_bit_cast(int, v))); }
; DI u32x4 pk8(f32x4 a, f32x4 b) { u32x4 w; w.x = pk2(a[0], a[1]); w.y = pk2(a[2], a[3]); w.z = pk2(b[0], b[1]); w.w = pk2(b[2], b[3]); return w; }
; DI void rope8(f32x4& v0, f32x4& v1, int row, int axis, int fq, int lane, const f32x2* rope) {
;     const int l = row & 4095, pos = axis ? (l & 63) : (l >> 6);
;     const f32x2* t = rope + pos * 16 + 8 * (fq & 1);
;     const float sgn = (fq < 2) ? -1.f : 1.f;
; #pragma unroll
;     for (int j = 0; j < 4; ++j) {
;         const float p0 = shx(v0[j], 32, lane), p1 = shx(v1[j], 32, lane);
;         const f32x2 c0 = t[j], c1 = t[4 + j];
;         v0[j] = v0[j] * c0.x + sgn * p0 * c0.y; v1[j] = v1[j] * c1.x + sgn * p1 * c1.y;
;     }
; }
; DI float row_rstd(const float* ssq, int row, int which) { const f32x4 a = *(const f32x4*)(ssq + (size_t)row * 16 + which * 8), b = *(const f32x4*)(ssq + (size_t)row * 16 + which * 8 + 4);
;     const float s = ((a[0] + a[1]) + (a[2] + a[3])) + ((b[0] + b[1]) + (b[2] + b[3])); return __builtin_amdgcn_rsqf(s * (1.f / 512.f) + EPS); }
;     DI void operator()(AccRef acc, const Unit& u, int wr, int wc, int fr, int fq) const {
;     ...
;             for (int m = 0; m < 4; ++m) { const int row = rowb + ai * 128 + m * 16; const float rs = row_rstd(ssq, row, 0) * scale;
; #pragma unroll
;                 for (int bj = 0; bj < 2; ++bj) { const int c32 = 256 * u.pn + 128 * bj + 32 * wc; f32x4 v0 = acc[ai][bj][m][0] * rs, v1 = acc[ai][bj][m][1] * rs;
;                     if (((c32 >> 6) % 3) == 2 && row < ML) rope8(v0, v1, row, (c32 >> 5) & 1, fq, fq * 16 + fr, rope);
;                     *(u32x4*)(Q + (size_t)row * 1536 + c32 + 8 * fq) = pk8(v0, v1); } }
.LBB0_664:
	s_or_b64 exec, exec, s[4:5]
	v_cvt_pk_bf16_f32 v50, v54, v55
	v_cvt_pk_bf16_f32 v51, v56, v57
	v_cvt_pk_bf16_f32 v52, v60, v61
	v_cvt_pk_bf16_f32 v53, v62, v63
	global_store_dwordx4 v[58:59], v[50:53], off offset:256
	v_cmp_gt_i32_e64 s[4:5], s51, v134
	s_and_b64 s[38:39], s[4:5], s[0:1]
	v_add_u32_e32 v50, 0x90, v134
	v_ashrrev_i32_e32 v51, 31, v50
	v_lshlrev_b64 v[52:53], 6, v[50:51]
	v_lshl_add_u64 v[56:57], s[12:13], 0, v[52:53]
	s_nop 0
	v_mov_b32_e32 v52, v234
	v_mov_b32_e32 v53, v235
	v_mov_b32_e32 v54, v236
	v_mov_b32_e32 v55, v237
	v_mov_b32_e32 v56, v238
	v_mov_b32_e32 v57, v239
	v_mov_b32_e32 v58, v240
	v_mov_b32_e32 v59, v241
	v_mov_b32_e32 v60, v52
	v_mov_b32_e32 v61, v56
	v_mov_b32_e32 v56, v53
	v_pk_add_f32 v[52:53], v[60:61], v[56:57]
	v_mov_b32_e32 v56, v54
	v_mov_b32_e32 v57, v58
	v_mov_b32_e32 v58, v55
	v_pk_add_f32 v[54:55], v[56:57], v[58:59]
	s_nop 0
	v_pk_add_f32 v[52:53], v[52:53], v[54:55]
	s_nop 0
	v_add_f32_e32 v0, v52, v53
	v_fmamk_f32 v0, v0, 0x3b000000, v193
	v_rsq_f32_e32 v0, v0
	s_nop 0
	v_mul_f32_e32 v52, 0x3dd53b94, v0
	v_lshrrev_b32_e32 v0, 6, v50
	v_cndmask_b32_e32 v0, v50, v0, vcc
	v_lshlrev_b32_e32 v0, 4, v0
	v_and_b32_e32 v0, 0x3f0, v0
	v_pk_mul_f32 v[54:55], v[48:49], v[52:53] op_sel_hi:[1,0]
	v_pk_mul_f32 v[46:47], v[46:47], v[52:53] op_sel_hi:[1,0]
	v_pk_mul_f32 v[56:57], v[44:45], v[52:53] op_sel_hi:[1,0]
	v_pk_mul_f32 v[48:49], v[42:43], v[52:53] op_sel_hi:[1,0]
	v_lshlrev_b32_e32 v0, 3, v0
	s_and_saveexec_b64 s[28:29], s[38:39]
	s_cbranch_execz .LBB0_666
	v_lshl_add_u64 v[42:43], s[16:17], 0, v[0:1]
	v_mov_b32_e32 v127, v1
	v_lshl_add_u64 v[66:67], v[42:43], 0, v[126:127]
	global_load_dwordx4 v[42:45], v[66:67], off offset:48
	global_load_dwordx4 v[58:61], v[66:67], off offset:16
	global_load_dwordx4 v[62:65], v[66:67], off offset:32
	s_nop 0
	global_load_dwordx4 v[66:69], v[66:67], off
	ds_bpermute_b32 v51, v131, v48
	ds_bpermute_b32 v70, v131, v46
	v_mov_b32_e32 v72, v48
	ds_bpermute_b32 v71, v131, v47
	s_waitcnt lgkmcnt(0)
	v_mul_f32_e32 v73, v130, v51
	ds_bpermute_b32 v51, v131, v56
	v_pk_mul_f32 v[70:71], v[130:131], v[70:71] op_sel_hi:[0,1]
	s_waitcnt vmcnt(1)
	v_mul_f32_e32 v48, v73, v63
	v_pk_fma_f32 v[62:63], v[72:73], v[62:63], v[48:49] op_sel_hi:[1,1,0]
	ds_bpermute_b32 v48, v131, v49
	s_waitcnt vmcnt(0)
	v_mov_b32_e32 v73, v68
	v_mov_b32_e32 v68, v67
	v_mov_b32_e32 v72, v66
	v_pk_mul_f32 v[66:67], v[70:71], v[68:69]
	s_waitcnt lgkmcnt(0)
	v_mul_f32_e32 v69, v130, v48
	v_mov_b32_e32 v68, v49
	v_mul_f32_e32 v48, v49, v64
	v_pk_fma_f32 v[48:49], v[68:69], v[64:65], v[48:49] op_sel_hi:[1,1,0]
	ds_bpermute_b32 v48, v131, v54
	v_mul_f32_e32 v65, v130, v51
	v_mul_f32_e32 v54, v54, v58
	v_mov_b32_e32 v64, v56
	v_pk_fma_f32 v[46:47], v[46:47], v[72:73], v[66:67]
	s_waitcnt lgkmcnt(0)
	v_mul_f32_e32 v48, v130, v48
	v_mul_f32_e32 v58, v48, v59
	v_mul_f32_e32 v48, v65, v43
	v_pk_fma_f32 v[42:43], v[64:65], v[42:43], v[48:49] op_sel_hi:[1,1,0]
	ds_bpermute_b32 v43, v131, v55
	ds_bpermute_b32 v48, v131, v57
	v_mov_b32_e32 v64, v55
	v_mov_b32_e32 v56, v42
	s_waitcnt lgkmcnt(1)
	v_mul_f32_e32 v65, v130, v43
	v_pk_mul_f32 v[60:61], v[64:65], v[60:61]
	s_nop 0
	v_mov_b32_e32 v55, v60
	v_mov_b32_e32 v59, v61
	v_pk_add_f32 v[54:55], v[54:55], v[58:59]
	s_waitcnt lgkmcnt(0)
	v_mul_f32_e32 v59, v130, v48
	v_mov_b32_e32 v58, v57
	v_mul_f32_e32 v48, v59, v45
	v_pk_fma_f32 v[44:45], v[58:59], v[44:45], v[48:49] op_sel_hi:[1,1,0]
	v_mov_b32_e32 v48, v62
	v_mov_b32_e32 v57, v44

; DI float shx(float v, int m, int lane) { return __builtin_bit_cast(float, __builtin_amdgcn_ds_bpermute((lane ^ m) << 2, __builtin_bit_cast(int, v))); }
; DI u32x4 pk8(f32x4 a, f32x4 b) { u32x4 w; w.x = pk2(a[0], a[1]); w.y = pk2(a[2], a[3]); w.z = pk2(b[0], b[1]); w.w = pk2(b[2], b[3]); return w; }
; DI void rope8(f32x4& v0, f32x4& v1, int row, int axis, int fq, int lane, const f32x2* rope) {
;     const int l = row & 4095, pos = axis ? (l & 63) : (l >> 6);
;     const f32x2* t = rope + pos * 16 + 8 * (fq & 1);
;     const float sgn = (fq < 2) ? -1.f : 1.f;
; #pragma unroll
;     for (int j = 0; j < 4; ++j) {
;         const float p0 = shx(v0[j], 32, lane), p1 = shx(v1[j], 32, lane);
;         const f32x2 c0 = t[j], c1 = t[4 + j];
;         v0[j] = v0[j] * c0.x + sgn * p0 * c0.y; v1[j] = v1[j] * c1.x + sgn * p1 * c1.y;
;     }
; }
; DI float row_rstd(const float* ssq, int row, int which) { const f32x4 a = *(const f32x4*)(ssq + (size_t)row * 16 + which * 8), b = *(const f32x4*)(ssq + (size_t)row * 16 + which * 8 + 4);
;     const float s = ((a[0] + a[1]) + (a[2] + a[3])) + ((b[0] + b[1]) + (b[2] + b[3])); return __builtin_amdgcn_rsqf(s * (1.f / 512.f) + EPS); }
;     DI void operator()(AccRef acc, const Unit& u, int wr, int wc, int fr, int fq) const {
;     ...
;             for (int m = 0; m < 4; ++m) { const int row = rowb + ai * 128 + m * 16; const float rs = row_rstd(ssq, row, 0) * scale;
; #pragma unroll
;                 for (int bj = 0; bj < 2; ++bj) { const int c32 = 256 * u.pn + 128 * bj + 32 * wc; f32x4 v0 = acc[ai][bj][m][0] * rs, v1 = acc[ai][bj][m][1] * rs;
;                     if (((c32 >> 6) % 3) == 2 && row < ML) rope8(v0, v1, row, (c32 >> 5) & 1, fq, fq * 16 + fr, rope);
;                     *(u32x4*)(Q + (size_t)row * 1536 + c32 + 8 * fq) = pk8(v0, v1); } }
.LBB0_668:
	s_or_b64 exec, exec, s[4:5]
	v_cvt_pk_bf16_f32 v34, v38, v39
	v_cvt_pk_bf16_f32 v35, v40, v41
	v_cvt_pk_bf16_f32 v36, v44, v45
	v_cvt_pk_bf16_f32 v37, v46, v47
	global_store_dwordx4 v[42:43], v[34:37], off offset:256
	v_cmp_gt_i32_e64 s[4:5], s69, v134
	s_and_b64 s[38:39], s[4:5], s[0:1]
	v_add_u32_e32 v34, 0xa0, v134
	v_ashrrev_i32_e32 v35, 31, v34
	v_lshlrev_b64 v[36:37], 6, v[34:35]
	v_lshl_add_u64 v[40:41], s[12:13], 0, v[36:37]
	s_nop 0
	v_mov_b32_e32 v36, v242
	v_mov_b32_e32 v37, v243
	v_mov_b32_e32 v38, v244
	v_mov_b32_e32 v39, v245
	v_mov_b32_e32 v40, v246
	v_mov_b32_e32 v41, v247
	v_mov_b32_e32 v42, v248
	v_mov_b32_e32 v43, v249
	v_mov_b32_e32 v44, v36
	v_mov_b32_e32 v45, v40
	v_mov_b32_e32 v40, v37
	v_pk_add_f32 v[36:37], v[44:45], v[40:41]
	v_mov_b32_e32 v40, v38
	v_mov_b32_e32 v41, v42
	v_mov_b32_e32 v42, v39
	v_pk_add_f32 v[38:39], v[40:41], v[42:43]
	s_nop 0
	v_pk_add_f32 v[36:37], v[36:37], v[38:39]
	s_nop 0
	v_add_f32_e32 v0, v36, v37
	v_fmamk_f32 v0, v0, 0x3b000000, v193
	v_rsq_f32_e32 v0, v0
	s_nop 0
	v_mul_f32_e32 v36, 0x3dd53b94, v0
	v_lshrrev_b32_e32 v0, 6, v34
	v_cndmask_b32_e32 v0, v34, v0, vcc
	v_lshlrev_b32_e32 v0, 4, v0
	v_and_b32_e32 v0, 0x3f0, v0
	v_pk_mul_f32 v[38:39], v[32:33], v[36:37] op_sel_hi:[1,0]
	v_pk_mul_f32 v[30:31], v[30:31], v[36:37] op_sel_hi:[1,0]
	v_pk_mul_f32 v[40:41], v[28:29], v[36:37] op_sel_hi:[1,0]
	v_pk_mul_f32 v[32:33], v[26:27], v[36:37] op_sel_hi:[1,0]
	v_lshlrev_b32_e32 v0, 3, v0
	s_and_saveexec_b64 s[28:29], s[38:39]
	s_cbranch_execz .LBB0_670
	v_lshl_add_u64 v[26:27], s[16:17], 0, v[0:1]
	v_mov_b32_e32 v127, v1
	v_lshl_add_u64 v[50:51], v[26:27], 0, v[126:127]
	global_load_dwordx4 v[26:29], v[50:51], off offset:48
	global_load_dwordx4 v[42:45], v[50:51], off offset:16
	global_load_dwordx4 v[46:49], v[50:51], off offset:32
	s_nop 0
	global_load_dwordx4 v[50:53], v[50:51], off
	ds_bpermute_b32 v35, v131, v32
	ds_bpermute_b32 v54, v131, v30
	v_mov_b32_e32 v56, v32
	ds_bpermute_b32 v55, v131, v31
	s_waitcnt lgkmcnt(0)
	v_mul_f32_e32 v57, v130, v35
	ds_bpermute_b32 v35, v131, v40
	v_pk_mul_f32 v[54:55], v[130:131], v[54:55] op_sel_hi:[0,1]
	s_waitcnt vmcnt(1)
	v_mul_f32_e32 v32, v57, v47
	v_pk_fma_f32 v[46:47], v[56:57], v[46:47], v[32:33] op_sel_hi:[1,1,0]
	ds_bpermute_b32 v32, v131, v33
	s_waitcnt vmcnt(0)
	v_mov_b32_e32 v57, v52
	v_mov_b32_e32 v52, v51
	v_mov_b32_e32 v56, v50
	v_pk_mul_f32 v[50:51], v[54:55], v[52:53]
	s_waitcnt lgkmcnt(0)
	v_mul_f32_e32 v53, v130, v32
	v_mov_b32_e32 v52, v33
	v_mul_f32_e32 v32, v33, v48
	v_pk_fma_f32 v[32:33], v[52:53], v[48:49], v[32:33] op_sel_hi:[1,1,0]
	ds_bpermute_b32 v32, v131, v38
	v_mul_f32_e32 v49, v130, v35
	v_mul_f32_e32 v38, v38, v42
	v_mov_b32_e32 v48, v40
	v_pk_fma_f32 v[30:31], v[30:31], v[56:57], v[50:51]
	s_waitcnt lgkmcnt(0)
	v_mul_f32_e32 v32, v130, v32
	v_mul_f32_e32 v42, v32, v43
	v_mul_f32_e32 v32, v49, v27
	v_pk_fma_f32 v[26:27], v[48:49], v[26:27], v[32:33] op_sel_hi:[1,1,0]
	ds_bpermute_b32 v27, v131, v39
	ds_bpermute_b32 v32, v131, v41
	v_mov_b32_e32 v48, v39
	v_mov_b32_e32 v40, v26
	s_waitcnt lgkmcnt(1)
	v_mul_f32_e32 v49, v130, v27
	v_pk_mul_f32 v[44:45], v[48:49], v[44:45]
	s_nop 0
	v_mov_b32_e32 v39, v44
	v_mov_b32_e32 v43, v45
	v_pk_add_f32 v[38:39], v[38:39], v[42:43]
	s_waitcnt lgkmcnt(0)
	v_mul_f32_e32 v43, v130, v32
	v_mov_b32_e32 v42, v41
	v_mul_f32_e32 v32, v43, v29
	v_pk_fma_f32 v[28:29], v[42:43], v[28:29], v[32:33] op_sel_hi:[1,1,0]
	v_mov_b32_e32 v32, v46
	v_mov_b32_e32 v41, v28

; DI float shx(float v, int m, int lane) { return __builtin_bit_cast(float, __builtin_amdgcn_ds_bpermute((lane ^ m) << 2, __builtin_bit_cast(int, v))); }
; DI u32x4 pk8(f32x4 a, f32x4 b) { u32x4 w; w.x = pk2(a[0], a[1]); w.y = pk2(a[2], a[3]); w.z = pk2(b[0], b[1]); w.w = pk2(b[2], b[3]); return w; }
; DI void rope8(f32x4& v0, f32x4& v1, int row, int axis, int fq, int lane, const f32x2* rope) {
;     const int l = row & 4095, pos = axis ? (l & 63) : (l >> 6);
;     const f32x2* t = rope + pos * 16 + 8 * (fq & 1);
;     const float sgn = (fq < 2) ? -1.f : 1.f;
; #pragma unroll
;     for (int j = 0; j < 4; ++j) {
;         const float p0 = shx(v0[j], 32, lane), p1 = shx(v1[j], 32, lane);
;         const f32x2 c0 = t[j], c1 = t[4 + j];
;         v0[j] = v0[j] * c0.x + sgn * p0 * c0.y; v1[j] = v1[j] * c1.x + sgn * p1 * c1.y;
;     }
; }
; DI float row_rstd(const float* ssq, int row, int which) { const f32x4 a = *(const f32x4*)(ssq + (size_t)row * 16 + which * 8), b = *(const f32x4*)(ssq + (size_t)row * 16 + which * 8 + 4);
;     const float s = ((a[0] + a[1]) + (a[2] + a[3])) + ((b[0] + b[1]) + (b[2] + b[3])); return __builtin_amdgcn_rsqf(s * (1.f / 512.f) + EPS); }
;     DI void operator()(AccRef acc, const Unit& u, int wr, int wc, int fr, int fq) const {
;     ...
;             for (int m = 0; m < 4; ++m) { const int row = rowb + ai * 128 + m * 16; const float rs = row_rstd(ssq, row, 0) * scale;
; #pragma unroll
;                 for (int bj = 0; bj < 2; ++bj) { const int c32 = 256 * u.pn + 128 * bj + 32 * wc; f32x4 v0 = acc[ai][bj][m][0] * rs, v1 = acc[ai][bj][m][1] * rs;
;                     if (((c32 >> 6) % 3) == 2 && row < ML) rope8(v0, v1, row, (c32 >> 5) & 1, fq, fq * 16 + fr, rope);
;                     *(u32x4*)(Q + (size_t)row * 1536 + c32 + 8 * fq) = pk8(v0, v1); } }
.LBB0_672:
	s_or_b64 exec, exec, s[4:5]
	v_cvt_pk_bf16_f32 v18, v22, v23
	v_cvt_pk_bf16_f32 v19, v24, v25
	v_cvt_pk_bf16_f32 v20, v28, v29
	v_cvt_pk_bf16_f32 v21, v30, v31
	global_store_dwordx4 v[26:27], v[18:21], off offset:256
	v_cmp_gt_i32_e64 s[4:5], s83, v134
	s_and_b64 s[28:29], s[4:5], s[0:1]
	v_add_u32_e32 v18, 0xb0, v134
	v_ashrrev_i32_e32 v19, 31, v18
	v_lshlrev_b64 v[20:21], 6, v[18:19]
	v_lshl_add_u64 v[24:25], s[12:13], 0, v[20:21]
	s_nop 0
	v_mov_b32_e32 v20, v250
	v_mov_b32_e32 v21, v251
	v_mov_b32_e32 v22, v252
	v_mov_b32_e32 v23, v253
	v_mov_b32_e32 v24, v166
	v_mov_b32_e32 v25, v167
	v_mov_b32_e32 v26, v168
	v_mov_b32_e32 v27, v169
	v_mov_b32_e32 v28, v20
	v_mov_b32_e32 v29, v24
	v_mov_b32_e32 v24, v21
	v_pk_add_f32 v[20:21], v[28:29], v[24:25]
	v_mov_b32_e32 v24, v22
	v_mov_b32_e32 v25, v26
	v_mov_b32_e32 v26, v23
	v_pk_add_f32 v[22:23], v[24:25], v[26:27]
	s_nop 0
	v_pk_add_f32 v[20:21], v[20:21], v[22:23]
	s_nop 0
	v_add_f32_e32 v0, v20, v21
	v_fmamk_f32 v0, v0, 0x3b000000, v193
	v_rsq_f32_e32 v0, v0
	s_nop 0
	v_mul_f32_e32 v20, 0x3dd53b94, v0
	v_lshrrev_b32_e32 v0, 6, v18
	v_cndmask_b32_e32 v0, v18, v0, vcc
	v_lshlrev_b32_e32 v0, 4, v0
	v_and_b32_e32 v0, 0x3f0, v0
	v_pk_mul_f32 v[22:23], v[16:17], v[20:21] op_sel_hi:[1,0]
	v_pk_mul_f32 v[14:15], v[14:15], v[20:21] op_sel_hi:[1,0]
	v_pk_mul_f32 v[24:25], v[12:13], v[20:21] op_sel_hi:[1,0]
	v_pk_mul_f32 v[16:17], v[10:11], v[20:21] op_sel_hi:[1,0]
	v_lshlrev_b32_e32 v0, 3, v0
	s_and_saveexec_b64 s[0:1], s[28:29]
	s_cbranch_execz .LBB0_674
	v_lshl_add_u64 v[10:11], s[16:17], 0, v[0:1]
	v_mov_b32_e32 v127, v1
	v_lshl_add_u64 v[34:35], v[10:11], 0, v[126:127]
	global_load_dwordx4 v[10:13], v[34:35], off offset:48
	global_load_dwordx4 v[26:29], v[34:35], off offset:16
	global_load_dwordx4 v[30:33], v[34:35], off offset:32
	s_nop 0
	global_load_dwordx4 v[34:37], v[34:35], off
	ds_bpermute_b32 v19, v131, v16
	ds_bpermute_b32 v38, v131, v14
	v_mov_b32_e32 v40, v16
	ds_bpermute_b32 v39, v131, v15
	s_waitcnt lgkmcnt(0)
	v_mul_f32_e32 v41, v130, v19
	ds_bpermute_b32 v19, v131, v24
	v_pk_mul_f32 v[38:39], v[130:131], v[38:39] op_sel_hi:[0,1]
	s_waitcnt vmcnt(1)
	v_mul_f32_e32 v16, v41, v31
	v_pk_fma_f32 v[30:31], v[40:41], v[30:31], v[16:17] op_sel_hi:[1,1,0]
	ds_bpermute_b32 v16, v131, v17
	s_waitcnt vmcnt(0)
	v_mov_b32_e32 v41, v36
	v_mov_b32_e32 v36, v35
	v_mov_b32_e32 v40, v34
	v_pk_mul_f32 v[34:35], v[38:39], v[36:37]
	s_waitcnt lgkmcnt(0)
	v_mul_f32_e32 v37, v130, v16
	v_mov_b32_e32 v36, v17
	v_mul_f32_e32 v16, v17, v32
	v_pk_fma_f32 v[16:17], v[36:37], v[32:33], v[16:17] op_sel_hi:[1,1,0]
	ds_bpermute_b32 v16, v131, v22
	v_mul_f32_e32 v33, v130, v19
	v_mul_f32_e32 v22, v22, v26
	v_mov_b32_e32 v32, v24
	v_pk_fma_f32 v[14:15], v[14:15], v[40:41], v[34:35]
	s_waitcnt lgkmcnt(0)
	v_mul_f32_e32 v16, v130, v16
	v_mul_f32_e32 v26, v16, v27
	v_mul_f32_e32 v16, v33, v11
	v_pk_fma_f32 v[10:11], v[32:33], v[10:11], v[16:17] op_sel_hi:[1,1,0]
	ds_bpermute_b32 v11, v131, v23
	ds_bpermute_b32 v16, v131, v25
	v_mov_b32_e32 v32, v23
	v_mov_b32_e32 v24, v10
	s_waitcnt lgkmcnt(1)
	v_mul_f32_e32 v33, v130, v11
	v_pk_mul_f32 v[28:29], v[32:33], v[28:29]
	s_nop 0
	v_mov_b32_e32 v23, v28
	v_mov_b32_e32 v27, v29
	v_pk_add_f32 v[22:23], v[22:23], v[26:27]
	s_waitcnt lgkmcnt(0)
	v_mul_f32_e32 v27, v130, v16
	v_mov_b32_e32 v26, v25
	v_mul_f32_e32 v16, v27, v13
	v_pk_fma_f32 v[12:13], v[26:27], v[12:13], v[16:17] op_sel_hi:[1,1,0]
	v_mov_b32_e32 v16, v30
	v_mov_b32_e32 v25, v12

; #define PG8_STAGE(bufoff, gbase, voff) do { _Pragma("unroll") for (int _i = 0; _i < 2; ++_i) \
;         __builtin_amdgcn_global_load_lds((const unsigned*)((const char*)(gbase) + (voff)[_i]), (LAS unsigned*)(lds + (bufoff) + ldsw + _i * 8192), 16, 0, 0); } while (0)
; #define PG8_LDA(dst, b, h) do { _Pragma("unroll") for (int m = 0; m < 4; ++m) _Pragma("unroll") for (int k = 0; k < 2; ++k) dst[m][k] = *(const LAS bf16x8*)(lds + PG8_SA(b, h) + aoff + m * 2048 + k * 1024); } while (0)
; #define PG8_LDB(dst, b, h) do { _Pragma("unroll") for (int n = 0; n < 2; ++n) _Pragma("unroll") for (int k = 0; k < 2; ++k) dst[n][k] = *(const LAS bf16x8*)(lds + PG8_SB(b, h) + boff + n * 2048 + k * 1024); } while (0)
; #define PG8_MMA(ai, bj, At, Bt) do { __builtin_amdgcn_s_setprio(1); _Pragma("unroll") for (int m = 0; m < 4; ++m) _Pragma("unroll") for (int n = 0; n < 2; ++n) _Pragma("unroll") for (int k = 0; k < 2; ++k) \
;         acc[ai][bj][m][n] = __builtin_amdgcn_mfma_f32_16x16x32_bf16(Bt[n][k], At[m][k], acc[ai][bj][m][n], 0, 0, 0); __builtin_amdgcn_s_setprio(0); } while (0)
; #define PG8_WAIT_L(n) asm volatile("s_waitcnt lgkmcnt(" #n ")" ::: "memory")
; #define PG8_BAR __builtin_amdgcn_s_barrier()
; #define PG8_SCHED __builtin_amdgcn_sched_barrier(0)
; template <class Epi, class SchedT>
; DI void gemm_phase(LAS unsigned char* lds, const Gemm g, const SchedT& S, const Epi& E) {
;     ...
;             PG8_LDB(B0, 0, 0); PG8_SCHED; PG8_LDA(At, 0, 0); PG8_STAGE(PG8_SA(1, 1), a1 + hstepA, voffA);
;             PG8_WAIT_L(8); PG8_BAR; PG8_WAIT_L(0); PG8_MMA(0, 0, At, B0); PG8_BAR; PG8_SCHED;
;             PG8_LDB(B1, 0, 1); PG8_STAGE(PG8_SB(0, 0), b2, voffB);
;             PG8_BAR; PG8_WAIT_L(0); PG8_MMA(0, 1, At, B1); PG8_BAR;
;             PG8_LDA(At, 0, 1); PG8_STAGE(PG8_SA(0, 0), a2, voffA);
;             PG8_BAR; PG8_WAIT_L(0); PG8_MMA(1, 0, At, B0); PG8_BAR; PG8_SCHED;
.LBB0_860:
	s_add_u32 s24, s22, 0xfff30080
	s_addc_u32 s25, s23, -1
	s_add_i32 s57, 0, 0x10000
	v_add_u32_e32 v152, s57, v146
	ds_read_b128 v[136:139], v152
	ds_read_b128 v[140:143], v152 offset:1024
	ds_read_b128 v[148:151], v152 offset:2048
	ds_read_b128 v[152:155], v152 offset:3072
	s_cmp_eq_u32 s53, 4
	s_cselect_b32 s27, s19, s25
	s_cselect_b32 s26, s18, s24
	s_cselect_b32 s25, s5, s39
	s_cselect_b32 s24, s17, s38
	v_lshl_add_u64 v[176:177], s[22:23], 0, v[0:1]
	s_add_i32 m0, s44, 0xc000
	ds_read_b128 v[156:159], v147
	ds_read_b128 v[160:163], v147 offset:1024
	ds_read_b128 v[164:167], v147 offset:2048
	ds_read_b128 v[168:171], v147 offset:3072
	ds_read_b128 v[172:175], v147 offset:4096
	ds_read_b128 v[184:187], v147 offset:5120
	ds_read_b128 v[188:191], v147 offset:6144
	ds_read_b128 v[202:205], v147 offset:7168
	global_load_lds_dwordx4 v[176:177], off
	v_lshl_add_u64 v[176:177], s[22:23], 0, v[132:133]
	s_add_i32 m0, s44, 0xe000
	s_nop 0
	global_load_lds_dwordx4 v[176:177], off
	s_waitcnt lgkmcnt(8)
	s_barrier
	s_waitcnt lgkmcnt(0)
	s_setprio 1
	s_waitcnt lgkmcnt(0)
	v_mfma_f32_16x16x32_bf16 v[126:129], v[136:139], v[156:159], v[126:129]
	v_mfma_f32_16x16x32_bf16 v[122:125], v[148:151], v[156:159], v[122:125]
	v_mfma_f32_16x16x32_bf16 v[110:113], v[136:139], v[164:167], v[110:113]
	v_mfma_f32_16x16x32_bf16 v[106:109], v[148:151], v[164:167], v[106:109]
	v_mfma_f32_16x16x32_bf16 v[94:97], v[136:139], v[172:175], v[94:97]
	v_mfma_f32_16x16x32_bf16 v[90:93], v[148:151], v[172:175], v[90:93]
	v_mfma_f32_16x16x32_bf16 v[78:81], v[136:139], v[188:191], v[78:81]
	v_mfma_f32_16x16x32_bf16 v[74:77], v[148:151], v[188:191], v[74:77]
	v_mfma_f32_16x16x32_bf16 v[126:129], v[140:143], v[160:163], v[126:129]
	v_mfma_f32_16x16x32_bf16 v[122:125], v[152:155], v[160:163], v[122:125]
	v_mfma_f32_16x16x32_bf16 v[110:113], v[140:143], v[168:171], v[110:113]
	v_mfma_f32_16x16x32_bf16 v[106:109], v[152:155], v[168:171], v[106:109]
	v_mfma_f32_16x16x32_bf16 v[94:97], v[140:143], v[184:187], v[94:97]
	v_mfma_f32_16x16x32_bf16 v[90:93], v[152:155], v[184:187], v[90:93]
	v_mfma_f32_16x16x32_bf16 v[78:81], v[140:143], v[202:205], v[78:81]
	v_mfma_f32_16x16x32_bf16 v[74:77], v[152:155], v[202:205], v[74:77]
	s_setprio 0
	s_barrier
	s_add_i32 s68, 0, 0x14000
	v_add_u32_e32 v176, s68, v146
	s_add_i32 s57, s57, s36
	ds_read_b128 v[206:209], v176
	ds_read_b128 v[210:213], v176 offset:1024
	ds_read_b128 v[214:217], v176 offset:2048
	ds_read_b128 v[218:221], v176 offset:3072
	v_lshl_add_u64 v[176:177], s[24:25], 0, v[130:131]
	s_mov_b32 m0, s57
	v_lshl_add_u64 v[178:179], s[24:25], 0, v[134:135]
	global_load_lds_dwordx4 v[176:177], off
	s_add_i32 m0, s57, 0x2000
	s_nop 0
	global_load_lds_dwordx4 v[178:179], off
	s_barrier
	s_waitcnt lgkmcnt(0)
	s_setprio 1
	s_waitcnt lgkmcnt(0)
	v_mfma_f32_16x16x32_bf16 v[118:121], v[206:209], v[156:159], v[118:121]
	v_mfma_f32_16x16x32_bf16 v[114:117], v[214:217], v[156:159], v[114:117]
	v_mfma_f32_16x16x32_bf16 v[102:105], v[206:209], v[164:167], v[102:105]
	v_mfma_f32_16x16x32_bf16 v[98:101], v[214:217], v[164:167], v[98:101]
	v_mfma_f32_16x16x32_bf16 v[86:89], v[206:209], v[172:175], v[86:89]
	v_mfma_f32_16x16x32_bf16 v[82:85], v[214:217], v[172:175], v[82:85]
	v_mfma_f32_16x16x32_bf16 v[70:73], v[206:209], v[188:191], v[70:73]
	v_mfma_f32_16x16x32_bf16 v[66:69], v[214:217], v[188:191], v[66:69]
	v_mfma_f32_16x16x32_bf16 v[118:121], v[210:213], v[160:163], v[118:121]
	v_mfma_f32_16x16x32_bf16 v[114:117], v[218:221], v[160:163], v[114:117]
	v_mfma_f32_16x16x32_bf16 v[102:105], v[210:213], v[168:171], v[102:105]
	v_mfma_f32_16x16x32_bf16 v[98:101], v[218:221], v[168:171], v[98:101]
	v_mfma_f32_16x16x32_bf16 v[86:89], v[210:213], v[184:187], v[86:89]
	v_mfma_f32_16x16x32_bf16 v[82:85], v[218:221], v[184:187], v[82:85]
	v_mfma_f32_16x16x32_bf16 v[70:73], v[210:213], v[202:205], v[70:73]
	v_mfma_f32_16x16x32_bf16 v[66:69], v[218:221], v[202:205], v[66:69]
	s_setprio 0
	s_mov_b32 m0, s44
	v_lshl_add_u64 v[180:181], s[26:27], 0, v[0:1]
	s_barrier
	ds_read_b128 v[156:159], v147 offset:16384
	ds_read_b128 v[160:163], v147 offset:17408
	ds_read_b128 v[164:167], v147 offset:18432
	ds_read_b128 v[168:171], v147 offset:19456
	ds_read_b128 v[172:175], v147 offset:20480
	ds_read_b128 v[184:187], v147 offset:21504
	ds_read_b128 v[188:191], v147 offset:22528
	ds_read_b128 v[202:205], v147 offset:23552
	global_load_lds_dwordx4 v[180:181], off
	v_lshl_add_u64 v[222:223], s[26:27], 0, v[132:133]
	s_mov_b32 m0, s45
	s_nop 0
	global_load_lds_dwordx4 v[222:223], off
	s_barrier
	s_waitcnt lgkmcnt(0)
	s_setprio 1
	s_waitcnt lgkmcnt(0)
	v_mfma_f32_16x16x32_bf16 v[62:65], v[136:139], v[156:159], v[62:65]
	v_mfma_f32_16x16x32_bf16 v[58:61], v[148:151], v[156:159], v[58:61]
	v_mfma_f32_16x16x32_bf16 v[46:49], v[136:139], v[164:167], v[46:49]
	v_mfma_f32_16x16x32_bf16 v[42:45], v[148:151], v[164:167], v[42:45]
	v_mfma_f32_16x16x32_bf16 v[30:33], v[136:139], v[172:175], v[30:33]
	v_mfma_f32_16x16x32_bf16 v[26:29], v[148:151], v[172:175], v[26:29]
	v_mfma_f32_16x16x32_bf16 v[14:17], v[136:139], v[188:191], v[14:17]
	v_mfma_f32_16x16x32_bf16 v[10:13], v[148:151], v[188:191], v[10:13]
	v_mfma_f32_16x16x32_bf16 v[62:65], v[140:143], v[160:163], v[62:65]
	v_mfma_f32_16x16x32_bf16 v[58:61], v[152:155], v[160:163], v[58:61]
	v_mfma_f32_16x16x32_bf16 v[46:49], v[140:143], v[168:171], v[46:49]
	v_mfma_f32_16x16x32_bf16 v[42:45], v[152:155], v[168:171], v[42:45]
	v_mfma_f32_16x16x32_bf16 v[30:33], v[140:143], v[184:187], v[30:33]
	v_mfma_f32_16x16x32_bf16 v[26:29], v[152:155], v[184:187], v[26:29]
	v_mfma_f32_16x16x32_bf16 v[14:17], v[140:143], v[202:205], v[14:17]
	v_mfma_f32_16x16x32_bf16 v[10:13], v[152:155], v[202:205], v[10:13]
	s_setprio 0
	s_barrier
; #define PG8_STAGE(bufoff, gbase, voff) do { _Pragma("unroll") for (int _i = 0; _i < 2; ++_i) \
;         __builtin_amdgcn_global_load_lds((const unsigned*)((const char*)(gbase) + (voff)[_i]), (LAS unsigned*)(lds + (bufoff) + ldsw + _i * 8192), 16, 0, 0); } while (0)
; #define PG8_LDA(dst, b, h) do { _Pragma("unroll") for (int m = 0; m < 4; ++m) _Pragma("unroll") for (int k = 0; k < 2; ++k) dst[m][k] = *(const LAS bf16x8*)(lds + PG8_SA(b, h) + aoff + m * 2048 + k * 1024); } while (0)
; #define PG8_LDB(dst, b, h) do { _Pragma("unroll") for (int n = 0; n < 2; ++n) _Pragma("unroll") for (int k = 0; k < 2; ++k) dst[n][k] = *(const LAS bf16x8*)(lds + PG8_SB(b, h) + boff + n * 2048 + k * 1024); } while (0)
; #define PG8_MMA(ai, bj, At, Bt) do { __builtin_amdgcn_s_setprio(1); _Pragma("unroll") for (int m = 0; m < 4; ++m) _Pragma("unroll") for (int n = 0; n < 2; ++n) _Pragma("unroll") for (int k = 0; k < 2; ++k) \
;         acc[ai][bj][m][n] = __builtin_amdgcn_mfma_f32_16x16x32_bf16(Bt[n][k], At[m][k], acc[ai][bj][m][n], 0, 0, 0); __builtin_amdgcn_s_setprio(0); } while (0)
; #define PG8_WAIT_V(n) asm volatile("s_waitcnt vmcnt(" #n ")" ::: "memory")
; #define PG8_WAIT_L(n) asm volatile("s_waitcnt lgkmcnt(" #n ")" ::: "memory")
; #define PG8_BAR __builtin_amdgcn_s_barrier()
; #define PG8_SCHED __builtin_amdgcn_sched_barrier(0)
; template <class Epi, class SchedT>
; DI void gemm_phase(LAS unsigned char* lds, const Gemm g, const SchedT& S, const Epi& E) {
;     ...
;             PG8_STAGE(PG8_SB(0, 1), b2 + hstepB, voffB);
;             PG8_WAIT_V(6); PG8_BAR; PG8_MMA(1, 1, At, B1); PG8_BAR;
;             PG8_LDB(B0, 1, 0); PG8_SCHED; PG8_LDA(At, 1, 0); PG8_STAGE(PG8_SA(0, 1), a2 + hstepA, voffA);
;             PG8_WAIT_L(8); PG8_BAR; PG8_WAIT_L(0); PG8_MMA(0, 0, At, B0); PG8_BAR; PG8_SCHED;
;             PG8_LDB(B1, 1, 1); PG8_STAGE(PG8_SB(1, 0), b3, voffB);
;             PG8_BAR; PG8_WAIT_L(0); PG8_MMA(0, 1, At, B1); PG8_BAR;
;             PG8_LDA(At, 1, 1); PG8_STAGE(PG8_SA(1, 0), a3, voffA);
;             PG8_BAR; PG8_WAIT_L(0); PG8_MMA(1, 0, At, B0); PG8_BAR; PG8_SCHED;
	s_add_u32 s66, s24, 0x20000
	s_addc_u32 s67, s25, 0
	s_add_i32 s57, s68, s36
	v_lshl_add_u64 v[136:137], s[66:67], 0, v[130:131]
	s_mov_b32 m0, s57
	s_nop 0
	global_load_lds_dwordx4 v[136:137], off
	v_lshl_add_u64 v[136:137], s[66:67], 0, v[134:135]
	s_add_i32 m0, s57, 0x2000
	s_nop 0
	global_load_lds_dwordx4 v[136:137], off
	s_waitcnt vmcnt(6)
	s_barrier
	s_setprio 1
	v_mfma_f32_16x16x32_bf16 v[54:57], v[206:209], v[156:159], v[54:57]
	v_mfma_f32_16x16x32_bf16 v[50:53], v[214:217], v[156:159], v[50:53]
	v_mfma_f32_16x16x32_bf16 v[38:41], v[206:209], v[164:167], v[38:41]
	v_mfma_f32_16x16x32_bf16 v[34:37], v[214:217], v[164:167], v[34:37]
	v_mfma_f32_16x16x32_bf16 v[22:25], v[206:209], v[172:175], v[22:25]
	v_mfma_f32_16x16x32_bf16 v[18:21], v[214:217], v[172:175], v[18:21]
	v_mfma_f32_16x16x32_bf16 v[6:9], v[206:209], v[188:191], v[6:9]
	v_mfma_f32_16x16x32_bf16 v[2:5], v[214:217], v[188:191], v[2:5]
	v_mfma_f32_16x16x32_bf16 v[54:57], v[210:213], v[160:163], v[54:57]
	v_mfma_f32_16x16x32_bf16 v[50:53], v[218:221], v[160:163], v[50:53]
	v_mfma_f32_16x16x32_bf16 v[38:41], v[210:213], v[168:171], v[38:41]
	v_mfma_f32_16x16x32_bf16 v[34:37], v[218:221], v[168:171], v[34:37]
	v_mfma_f32_16x16x32_bf16 v[22:25], v[210:213], v[184:187], v[22:25]
	v_mfma_f32_16x16x32_bf16 v[18:21], v[218:221], v[184:187], v[18:21]
	v_mfma_f32_16x16x32_bf16 v[6:9], v[210:213], v[202:205], v[6:9]
	v_mfma_f32_16x16x32_bf16 v[2:5], v[218:221], v[202:205], v[2:5]
	s_setprio 0
	s_add_i32 s57, 0, 0x18000
	v_add_u32_e32 v152, s57, v146
	s_barrier
	ds_read_b128 v[136:139], v152
	ds_read_b128 v[140:143], v152 offset:1024
	ds_read_b128 v[148:151], v152 offset:2048
	ds_read_b128 v[152:155], v152 offset:3072
	s_add_u32 s26, s26, 0xd0000
	s_addc_u32 s27, s27, 0
	s_mov_b32 m0, s46
	v_lshl_add_u64 v[206:207], s[26:27], 0, v[0:1]
	ds_read_b128 v[156:159], v147 offset:32768
	ds_read_b128 v[160:163], v147 offset:33792
	ds_read_b128 v[164:167], v147 offset:34816
	ds_read_b128 v[168:171], v147 offset:35840
	ds_read_b128 v[172:175], v147 offset:36864
	ds_read_b128 v[184:187], v147 offset:37888
	ds_read_b128 v[188:191], v147 offset:38912
	ds_read_b128 v[202:205], v147 offset:39936
	global_load_lds_dwordx4 v[206:207], off
	v_lshl_add_u64 v[206:207], s[26:27], 0, v[132:133]
	s_mov_b32 m0, s48
	s_nop 0
	global_load_lds_dwordx4 v[206:207], off
	s_waitcnt lgkmcnt(8)
	s_barrier
	s_waitcnt lgkmcnt(0)
	s_setprio 1
	s_waitcnt lgkmcnt(0)
	v_mfma_f32_16x16x32_bf16 v[126:129], v[136:139], v[156:159], v[126:129]
	v_mfma_f32_16x16x32_bf16 v[122:125], v[148:151], v[156:159], v[122:125]
	v_mfma_f32_16x16x32_bf16 v[110:113], v[136:139], v[164:167], v[110:113]
	v_mfma_f32_16x16x32_bf16 v[106:109], v[148:151], v[164:167], v[106:109]
	v_mfma_f32_16x16x32_bf16 v[94:97], v[136:139], v[172:175], v[94:97]
	v_mfma_f32_16x16x32_bf16 v[90:93], v[148:151], v[172:175], v[90:93]
	v_mfma_f32_16x16x32_bf16 v[78:81], v[136:139], v[188:191], v[78:81]
	v_mfma_f32_16x16x32_bf16 v[74:77], v[148:151], v[188:191], v[74:77]
	v_mfma_f32_16x16x32_bf16 v[126:129], v[140:143], v[160:163], v[126:129]
	v_mfma_f32_16x16x32_bf16 v[122:125], v[152:155], v[160:163], v[122:125]
	v_mfma_f32_16x16x32_bf16 v[110:113], v[140:143], v[168:171], v[110:113]
	v_mfma_f32_16x16x32_bf16 v[106:109], v[152:155], v[168:171], v[106:109]
	v_mfma_f32_16x16x32_bf16 v[94:97], v[140:143], v[184:187], v[94:97]
	v_mfma_f32_16x16x32_bf16 v[90:93], v[152:155], v[184:187], v[90:93]
	v_mfma_f32_16x16x32_bf16 v[78:81], v[140:143], v[202:205], v[78:81]
	v_mfma_f32_16x16x32_bf16 v[74:77], v[152:155], v[202:205], v[74:77]
	s_setprio 0
	s_barrier
	s_add_i32 s26, 0, 0x1c000
	s_add_i32 s27, s57, s36
	v_add_u32_e32 v182, s26, v146
	v_lshl_add_u64 v[176:177], v[176:177], 0, s[90:91]
	s_mov_b32 m0, s27
	ds_read_b128 v[206:209], v182
	ds_read_b128 v[210:213], v182 offset:1024
	ds_read_b128 v[214:217], v182 offset:2048
	ds_read_b128 v[218:221], v182 offset:3072
	global_load_lds_dwordx4 v[176:177], off
	v_lshl_add_u64 v[176:177], v[178:179], 0, s[90:91]
	s_add_i32 m0, s27, 0x2000
	s_nop 0
	global_load_lds_dwordx4 v[176:177], off
	s_barrier
	s_waitcnt lgkmcnt(0)
	s_setprio 1
	s_waitcnt lgkmcnt(0)
	v_mfma_f32_16x16x32_bf16 v[118:121], v[206:209], v[156:159], v[118:121]
	v_mfma_f32_16x16x32_bf16 v[114:117], v[214:217], v[156:159], v[114:117]
	v_mfma_f32_16x16x32_bf16 v[102:105], v[206:209], v[164:167], v[102:105]
	v_mfma_f32_16x16x32_bf16 v[98:101], v[214:217], v[164:167], v[98:101]
	v_mfma_f32_16x16x32_bf16 v[86:89], v[206:209], v[172:175], v[86:89]
	v_mfma_f32_16x16x32_bf16 v[82:85], v[214:217], v[172:175], v[82:85]
	v_mfma_f32_16x16x32_bf16 v[70:73], v[206:209], v[188:191], v[70:73]
	v_mfma_f32_16x16x32_bf16 v[66:69], v[214:217], v[188:191], v[66:69]
	v_mfma_f32_16x16x32_bf16 v[118:121], v[210:213], v[160:163], v[118:121]
	v_mfma_f32_16x16x32_bf16 v[114:117], v[218:221], v[160:163], v[114:117]
	v_mfma_f32_16x16x32_bf16 v[102:105], v[210:213], v[168:171], v[102:105]
	v_mfma_f32_16x16x32_bf16 v[98:101], v[218:221], v[168:171], v[98:101]
	v_mfma_f32_16x16x32_bf16 v[86:89], v[210:213], v[184:187], v[86:89]
	v_mfma_f32_16x16x32_bf16 v[82:85], v[218:221], v[184:187], v[82:85]
	v_mfma_f32_16x16x32_bf16 v[70:73], v[210:213], v[202:205], v[70:73]
	v_mfma_f32_16x16x32_bf16 v[66:69], v[218:221], v[202:205], v[66:69]
	s_setprio 0
	s_mov_b32 m0, s52
	v_lshl_add_u64 v[176:177], v[180:181], 0, s[90:91]
	s_barrier
	ds_read_b128 v[156:159], v147 offset:49152
	ds_read_b128 v[160:163], v147 offset:50176
	ds_read_b128 v[164:167], v147 offset:51200
	ds_read_b128 v[168:171], v147 offset:52224
	ds_read_b128 v[172:175], v147 offset:53248
	ds_read_b128 v[184:187], v147 offset:54272
	ds_read_b128 v[188:191], v147 offset:55296
	ds_read_b128 v[202:205], v147 offset:56320
	global_load_lds_dwordx4 v[176:177], off
	v_lshl_add_u64 v[176:177], v[222:223], 0, s[90:91]
	s_mov_b32 m0, s54
	s_nop 0
	global_load_lds_dwordx4 v[176:177], off
	s_barrier
; DI bf16_t f2bf(float a) { return (bf16_t)(pk2(a, 0.f) & 0xffffu); }
; DI u32x4 pk8(f32x4 a, f32x4 b) { u32x4 w; w.x = pk2(a[0], a[1]); w.y = pk2(a[2], a[3]); w.z = pk2(b[0], b[1]); w.w = pk2(b[2], b[3]); return w; }
; #define PG8_STAGE(bufoff, gbase, voff) do { _Pragma("unroll") for (int _i = 0; _i < 2; ++_i) \
;         __builtin_amdgcn_global_load_lds((const unsigned*)((const char*)(gbase) + (voff)[_i]), (LAS unsigned*)(lds + (bufoff) + ldsw + _i * 8192), 16, 0, 0); } while (0)
; #define PG8_LDA(dst, b, h) do { _Pragma("unroll") for (int m = 0; m < 4; ++m) _Pragma("unroll") for (int k = 0; k < 2; ++k) dst[m][k] = *(const LAS bf16x8*)(lds + PG8_SA(b, h) + aoff + m * 2048 + k * 1024); } while (0)
; #define PG8_WAIT_V(n) asm volatile("s_waitcnt vmcnt(" #n ")" ::: "memory")
; #define PG8_WAIT_L(n) asm volatile("s_waitcnt lgkmcnt(" #n ")" ::: "memory")
; #define PG8_BAR __builtin_amdgcn_s_barrier()
; #define PG8_SCHED __builtin_amdgcn_sched_barrier(0)
; template <class Epi, class SchedT>
; DI void gemm_phase(LAS unsigned char* lds, const Gemm g, const SchedT& S, const Epi& E) {
;     ...
;             PG8_LDA(At, 1, 1); PG8_STAGE(PG8_SA(1, 0), a3, voffA);
;             PG8_BAR; PG8_WAIT_L(0); PG8_MMA(1, 0, At, B0); PG8_BAR; PG8_SCHED;
;             PG8_STAGE(PG8_SB(1, 1), b3 + hstepB, voffB);
;             PG8_WAIT_V(6); PG8_BAR; PG8_MMA(1, 1, At, B1); PG8_BAR;
;     DI void operator()(AccRef acc, const Unit& u, int wr, int wc, int fr, int fq) const {
;         const int pn = u.pn, rowb = u.pm * 256 + wr * 64 + fr;
; #pragma unroll
;         for (int ai = 0; ai < 2; ++ai)
; #pragma unroll
;             for (int m = 0; m < 4; ++m) { const int row = rowb + ai * 128 + m * 16; const float rs = row_rstd(ssq, row, 1); int b, key; row_bk(row, b, key);
; #pragma unroll
;                 for (int bj = 0; bj < 2; ++bj) {
;                     if (pn < 4) { *(u32x4*)(KN + (size_t)row * 1024 + 256 * pn + 128 * bj + 32 * wc + 8 * fq) = pk8(acc[ai][bj][m][0] * rs, acc[ai][bj][m][1] * rs); }
;                     else { const int h = 2 * (pn - 4) + bj;
; #pragma unroll
;                         for (int n = 0; n < 2; ++n) { bf16_t* dst = VT + ((size_t)((b * 8 + h) * 128 + 32 * wc + 8 * fq + 4 * n)) * KEYS + key;
; #pragma unroll
;                             for (int j = 0; j < 4; ++j) dst[(size_t)j * KEYS] = f2bf(acc[ai][bj][m][n][j] * rs); } } } }
	s_waitcnt lgkmcnt(0)
	s_setprio 1
	s_waitcnt lgkmcnt(0)
	v_mfma_f32_16x16x32_bf16 v[62:65], v[136:139], v[156:159], v[62:65]
	v_mfma_f32_16x16x32_bf16 v[58:61], v[148:151], v[156:159], v[58:61]
	v_mfma_f32_16x16x32_bf16 v[46:49], v[136:139], v[164:167], v[46:49]
	v_mfma_f32_16x16x32_bf16 v[42:45], v[148:151], v[164:167], v[42:45]
	v_mfma_f32_16x16x32_bf16 v[30:33], v[136:139], v[172:175], v[30:33]
	v_mfma_f32_16x16x32_bf16 v[26:29], v[148:151], v[172:175], v[26:29]
	v_mfma_f32_16x16x32_bf16 v[14:17], v[136:139], v[188:191], v[14:17]
	v_mfma_f32_16x16x32_bf16 v[10:13], v[148:151], v[188:191], v[10:13]
	v_mfma_f32_16x16x32_bf16 v[62:65], v[140:143], v[160:163], v[62:65]
	v_mfma_f32_16x16x32_bf16 v[58:61], v[152:155], v[160:163], v[58:61]
	v_mfma_f32_16x16x32_bf16 v[46:49], v[140:143], v[168:171], v[46:49]
	v_mfma_f32_16x16x32_bf16 v[42:45], v[152:155], v[168:171], v[42:45]
	v_mfma_f32_16x16x32_bf16 v[30:33], v[140:143], v[184:187], v[30:33]
	v_mfma_f32_16x16x32_bf16 v[26:29], v[152:155], v[184:187], v[26:29]
	v_mfma_f32_16x16x32_bf16 v[14:17], v[140:143], v[202:205], v[14:17]
	v_mfma_f32_16x16x32_bf16 v[10:13], v[152:155], v[202:205], v[10:13]
	s_setprio 0
	s_barrier
	s_add_u32 s24, s24, 0x20080
	s_addc_u32 s25, s25, 0
	s_add_i32 s26, s26, s36
	v_lshl_add_u64 v[136:137], s[24:25], 0, v[130:131]
	s_mov_b32 m0, s26
	s_nop 0
	global_load_lds_dwordx4 v[136:137], off
	v_lshl_add_u64 v[136:137], s[24:25], 0, v[134:135]
	s_add_i32 m0, s26, 0x2000
	s_nop 0
	global_load_lds_dwordx4 v[136:137], off
	s_waitcnt vmcnt(6)
	s_barrier
	s_setprio 1
	v_mfma_f32_16x16x32_bf16 v[54:57], v[206:209], v[156:159], v[54:57]
	v_mfma_f32_16x16x32_bf16 v[50:53], v[214:217], v[156:159], v[50:53]
	v_mfma_f32_16x16x32_bf16 v[38:41], v[206:209], v[164:167], v[38:41]
	v_mfma_f32_16x16x32_bf16 v[34:37], v[214:217], v[164:167], v[34:37]
	v_mfma_f32_16x16x32_bf16 v[22:25], v[206:209], v[172:175], v[22:25]
	v_mfma_f32_16x16x32_bf16 v[18:21], v[214:217], v[172:175], v[18:21]
	v_mfma_f32_16x16x32_bf16 v[6:9], v[206:209], v[188:191], v[6:9]
	v_mfma_f32_16x16x32_bf16 v[2:5], v[214:217], v[188:191], v[2:5]
	v_mfma_f32_16x16x32_bf16 v[54:57], v[210:213], v[160:163], v[54:57]
	v_mfma_f32_16x16x32_bf16 v[50:53], v[218:221], v[160:163], v[50:53]
	v_mfma_f32_16x16x32_bf16 v[38:41], v[210:213], v[168:171], v[38:41]
	v_mfma_f32_16x16x32_bf16 v[34:37], v[218:221], v[168:171], v[34:37]
	v_mfma_f32_16x16x32_bf16 v[22:25], v[210:213], v[184:187], v[22:25]
	v_mfma_f32_16x16x32_bf16 v[18:21], v[218:221], v[184:187], v[18:21]
	v_mfma_f32_16x16x32_bf16 v[6:9], v[210:213], v[202:205], v[6:9]
	v_mfma_f32_16x16x32_bf16 v[2:5], v[218:221], v[202:205], v[2:5]
	s_setprio 0
	s_add_i32 s53, s53, 2
	s_add_u32 s22, s22, 0x100
	s_addc_u32 s23, s23, 0
	s_add_u32 s38, s38, 0x100
	s_addc_u32 s39, s39, 0
	s_cmp_gt_u32 s53, 5
	s_barrier
	s_cbranch_scc0 .LBB0_860
	v_mov_b32_e32 v139, v145
	s_mov_b32 s5, s49
	v_mov_b32_e32 v0, v144
	s_mov_b32 s17, s35
	s_lshl_b32 s22, s33, 8
	s_lshl_b32 s17, s17, 6
	s_add_i32 s17, s17, s22
	v_add_u32_e32 v142, s17, v0
	v_ashrrev_i32_e32 v143, 31, v142
	v_lshlrev_b64 v[130:131], 6, v[142:143]
	v_lshl_add_u64 v[134:135], s[12:13], 0, v[130:131]
	v_mov_b32_e32 v170, v134
	v_mov_b32_e32 v171, v135
	global_load_dwordx4 v[130:133], v[134:135], off offset:48
	s_nop 0
	global_load_dwordx4 v[134:137], v[134:135], off offset:32
	s_mov_b64 s[98:99], 0x2000
	v_lshl_add_u64 v[172:173], v[170:171], 0, s[98:99]
	global_load_dwordx4 v[202:205], v[170:171], off offset:1072
	global_load_dwordx4 v[206:209], v[170:171], off offset:1056
	global_load_dwordx4 v[210:213], v[170:171], off offset:2096
	global_load_dwordx4 v[214:217], v[170:171], off offset:2080
	global_load_dwordx4 v[218:221], v[170:171], off offset:3120
	global_load_dwordx4 v[222:225], v[170:171], off offset:3104
	global_load_dwordx4 v[226:229], v[172:173], off offset:48
	global_load_dwordx4 v[230:233], v[172:173], off offset:32
	global_load_dwordx4 v[234:237], v[172:173], off offset:1072
	global_load_dwordx4 v[238:241], v[172:173], off offset:1056
	global_load_dwordx4 v[242:245], v[172:173], off offset:2096
	global_load_dwordx4 v[246:249], v[172:173], off offset:2080
	global_load_dwordx4 v[250:253], v[172:173], off offset:3120
	global_load_dwordx4 v[166:169], v[172:173], off offset:3104
	v_cmp_lt_i32_e32 vcc, s84, v142
	s_and_saveexec_b64 s[22:23], vcc
	s_xor_b64 s[22:23], exec, s[22:23]
	v_add_u32_e32 v0, 0xffffc000, v142
	v_lshrrev_b32_e32 v141, 8, v0
	v_or_b32_sdwa v0, v142, s86 dst_sel:DWORD dst_unused:UNUSED_PAD src0_sel:BYTE_0 src1_sel:DWORD
	s_andn2_saveexec_b64 s[22:23], s[22:23]
	v_ashrrev_i32_e32 v141, 12, v142
	v_and_b32_e32 v0, 0xfff, v142
	s_or_b64 exec, exec, s[22:23]
	s_waitcnt vmcnt(0)
	v_add_f32_e32 v134, v134, v135
	v_add_f32_e32 v135, v136, v137
	v_add_f32_e32 v130, v130, v131
	v_add_f32_e32 v131, v132, v133
	v_add_f32_e32 v134, v134, v135
	v_add_f32_e32 v130, v130, v131
	v_add_f32_e32 v130, v134, v130
	v_fmamk_f32 v130, v130, 0x3b000000, v193
	v_rsq_f32_e32 v130, v130
	s_cmp_gt_i32 s4, 3
	v_lshlrev_b32_e64 v138, 5, s5
	v_lshlrev_b32_e32 v140, 3, v139
	s_cselect_b64 s[24:25], -1, 0
	s_lshl_b32 s17, s4, 1
	v_add_u32_e32 v148, v140, v138
	s_add_i32 s17, s17, 0x1fffff8
	v_lshl_add_u32 v136, v141, 10, v148
	s_mov_b64 s[26:27], -1
	s_and_b64 vcc, exec, s[24:25]
	v_lshl_add_u64 v[132:133], v[0:1], 1, s[14:15]
	s_cbranch_vccz .LBB0_867
	v_lshl_add_u32 v0, s17, 7, v136
	v_mul_f32_e32 v131, v126, v130
	v_mad_i64_i32 v[134:135], s[22:23], v0, s85, v[132:133]
	v_cvt_pk_bf16_f32 v131, v131, s0
	global_store_short v[134:135], v131, off
	v_mul_f32_e32 v131, v127, v130
	v_add_co_u32_e32 v150, vcc, 0x2000, v134
	v_cvt_pk_bf16_f32 v131, v131, s0
	s_nop 0
	v_addc_co_u32_e32 v151, vcc, 0, v135, vcc
	global_store_short v[150:151], v131, off offset:512
	v_mul_f32_e32 v131, v128, v130
	v_add_co_u32_e32 v150, vcc, s72, v134
	v_cvt_pk_bf16_f32 v131, v131, s0
	s_nop 0
	v_addc_co_u32_e32 v151, vcc, 0, v135, vcc
	global_store_short v[150:151], v131, off offset:1024
	v_mul_f32_e32 v131, v129, v130
	v_add_co_u32_e32 v134, vcc, 0x6000, v134
	v_cvt_pk_bf16_f32 v131, v131, s0
	s_nop 0
	v_addc_co_u32_e32 v135, vcc, 0, v135, vcc
	v_or_b32_e32 v0, 4, v0
	global_store_short v[134:135], v131, off offset:1536
	v_mad_i64_i32 v[134:135], s[22:23], v0, s85, v[132:133]
	v_mul_f32_e32 v0, v122, v130
	v_cvt_pk_bf16_f32 v0, v0, s0
	global_store_short v[134:135], v0, off
	v_mul_f32_e32 v0, v123, v130
	v_add_co_u32_e32 v150, vcc, 0x2000, v134
	v_cvt_pk_bf16_f32 v0, v0, s0
	s_nop 0
	v_addc_co_u32_e32 v151, vcc, 0, v135, vcc
	global_store_short v[150:151], v0, off offset:512
	v_mul_f32_e32 v0, v124, v130
	v_add_co_u32_e32 v150, vcc, 0x4000, v134
	v_cvt_pk_bf16_f32 v0, v0, s0
	s_nop 0
	v_addc_co_u32_e32 v151, vcc, 0, v135, vcc
	global_store_short v[150:151], v0, off offset:1024
	v_mul_f32_e32 v0, v125, v130
	v_add_co_u32_e32 v134, vcc, 0x6000, v134
	v_cvt_pk_bf16_f32 v0, v0, s0
	s_nop 0
	v_addc_co_u32_e32 v135, vcc, 0, v135, vcc
	global_store_short v[134:135], v0, off offset:1536
	s_mov_b64 s[26:27], 0

; DI bf16_t f2bf(float a) { return (bf16_t)(pk2(a, 0.f) & 0xffffu); }
; DI u32x4 pk8(f32x4 a, f32x4 b) { u32x4 w; w.x = pk2(a[0], a[1]); w.y = pk2(a[2], a[3]); w.z = pk2(b[0], b[1]); w.w = pk2(b[2], b[3]); return w; }
; DI void row_bk(int row, int& b, int& key) { if (row < ML) { b = row >> 12; key = row & 4095; } else { const int rc = row - ML; b = rc >> 8; key = SEQ + (rc & 255); } }
; DI float row_rstd(const float* ssq, int row, int which) { const f32x4 a = *(const f32x4*)(ssq + (size_t)row * 16 + which * 8), b = *(const f32x4*)(ssq + (size_t)row * 16 + which * 8 + 4);
;     const float s = ((a[0] + a[1]) + (a[2] + a[3])) + ((b[0] + b[1]) + (b[2] + b[3])); return __builtin_amdgcn_rsqf(s * (1.f / 512.f) + EPS); }
;     DI void operator()(AccRef acc, const Unit& u, int wr, int wc, int fr, int fq) const {
;     ...
;             for (int m = 0; m < 4; ++m) { const int row = rowb + ai * 128 + m * 16; const float rs = row_rstd(ssq, row, 1); int b, key; row_bk(row, b, key);
; #pragma unroll
;                 for (int bj = 0; bj < 2; ++bj) {
;                     if (pn < 4) { *(u32x4*)(KN + (size_t)row * 1024 + 256 * pn + 128 * bj + 32 * wc + 8 * fq) = pk8(acc[ai][bj][m][0] * rs, acc[ai][bj][m][1] * rs); }
;                     else { const int h = 2 * (pn - 4) + bj;
; #pragma unroll
;                         for (int n = 0; n < 2; ++n) { bf16_t* dst = VT + ((size_t)((b * 8 + h) * 128 + 32 * wc + 8 * fq + 4 * n)) * KEYS + key;
; #pragma unroll
;                             for (int j = 0; j < 4; ++j) dst[(size_t)j * KEYS] = f2bf(acc[ai][bj][m][n][j] * rs); } } } }
.LBB0_873:
	v_add_u32_e32 v122, 16, v142
	v_ashrrev_i32_e32 v123, 31, v122
	v_lshlrev_b64 v[114:115], 6, v[122:123]
	v_lshl_add_u64 v[118:119], s[12:13], 0, v[114:115]
	s_nop 0
	s_movk_i32 s24, 0x3fef
	v_cmp_lt_i32_e32 vcc, s24, v142
	s_and_saveexec_b64 s[24:25], vcc
	s_xor_b64 s[24:25], exec, s[24:25]
	v_add_u32_e32 v0, 0xffffc010, v142
	v_lshrrev_b32_e32 v124, 8, v0
	v_or_b32_sdwa v0, v122, s86 dst_sel:DWORD dst_unused:UNUSED_PAD src0_sel:BYTE_0 src1_sel:DWORD
	s_andn2_saveexec_b64 s[24:25], s[24:25]
	v_ashrrev_i32_e32 v124, 12, v122
	v_and_b32_e32 v0, 0xfff, v122
	s_or_b64 exec, exec, s[24:25]
	v_mov_b32_e32 v114, v202
	v_mov_b32_e32 v115, v203
	v_mov_b32_e32 v116, v204
	v_mov_b32_e32 v117, v205
	v_mov_b32_e32 v118, v206
	v_mov_b32_e32 v119, v207
	v_mov_b32_e32 v120, v208
	v_mov_b32_e32 v121, v209
	v_add_f32_e32 v118, v118, v119
	v_add_f32_e32 v119, v120, v121
	v_add_f32_e32 v114, v114, v115
	v_add_f32_e32 v115, v116, v117
	v_add_f32_e32 v118, v118, v119
	v_add_f32_e32 v114, v114, v115
	v_add_f32_e32 v114, v118, v114
	v_fmamk_f32 v114, v114, 0x3b000000, v193
	v_rsq_f32_e32 v114, v114
	v_lshl_add_u32 v120, v124, 10, v148
	s_mov_b64 s[24:25], -1
	s_and_b64 vcc, exec, s[4:5]
	v_lshl_add_u64 v[116:117], v[0:1], 1, s[14:15]
	s_cbranch_vccnz .LBB0_879
	v_lshl_add_u32 v0, s17, 7, v120
	v_mul_f32_e32 v115, v110, v114
	v_mad_i64_i32 v[118:119], s[24:25], v0, s85, v[116:117]
	v_cvt_pk_bf16_f32 v115, v115, s0
	global_store_short v[118:119], v115, off
	v_mul_f32_e32 v115, v111, v114
	v_add_co_u32_e32 v124, vcc, 0x2000, v118
	v_cvt_pk_bf16_f32 v115, v115, s0
	s_nop 0
	v_addc_co_u32_e32 v125, vcc, 0, v119, vcc
	global_store_short v[124:125], v115, off offset:512
	v_mul_f32_e32 v115, v112, v114
	v_add_co_u32_e32 v124, vcc, s72, v118
	v_cvt_pk_bf16_f32 v115, v115, s0
	s_nop 0
	v_addc_co_u32_e32 v125, vcc, 0, v119, vcc
	global_store_short v[124:125], v115, off offset:1024
	v_mul_f32_e32 v115, v113, v114
	v_add_co_u32_e32 v118, vcc, 0x6000, v118
	v_cvt_pk_bf16_f32 v115, v115, s0
	s_nop 0
	v_addc_co_u32_e32 v119, vcc, 0, v119, vcc
	v_or_b32_e32 v0, 4, v0
	global_store_short v[118:119], v115, off offset:1536
	v_mad_i64_i32 v[118:119], s[24:25], v0, s85, v[116:117]
	v_mul_f32_e32 v0, v106, v114
	v_cvt_pk_bf16_f32 v0, v0, s0
	global_store_short v[118:119], v0, off
	v_mul_f32_e32 v0, v107, v114
	v_add_co_u32_e32 v124, vcc, 0x2000, v118
	v_cvt_pk_bf16_f32 v0, v0, s0
	s_nop 0
	v_addc_co_u32_e32 v125, vcc, 0, v119, vcc
	global_store_short v[124:125], v0, off offset:512
	v_mul_f32_e32 v0, v108, v114
	v_add_co_u32_e32 v124, vcc, 0x4000, v118
	v_cvt_pk_bf16_f32 v0, v0, s0
	s_nop 0
	v_addc_co_u32_e32 v125, vcc, 0, v119, vcc
	global_store_short v[124:125], v0, off offset:1024
	v_mul_f32_e32 v0, v109, v114
	v_add_co_u32_e32 v118, vcc, 0x6000, v118
	v_cvt_pk_bf16_f32 v0, v0, s0
	s_nop 0
	v_addc_co_u32_e32 v119, vcc, 0, v119, vcc
	s_mov_b64 s[24:25], 0
	global_store_short v[118:119], v0, off offset:1536

; DI bf16_t f2bf(float a) { return (bf16_t)(pk2(a, 0.f) & 0xffffu); }
; DI u32x4 pk8(f32x4 a, f32x4 b) { u32x4 w; w.x = pk2(a[0], a[1]); w.y = pk2(a[2], a[3]); w.z = pk2(b[0], b[1]); w.w = pk2(b[2], b[3]); return w; }
; DI void row_bk(int row, int& b, int& key) { if (row < ML) { b = row >> 12; key = row & 4095; } else { const int rc = row - ML; b = rc >> 8; key = SEQ + (rc & 255); } }
; DI float row_rstd(const float* ssq, int row, int which) { const f32x4 a = *(const f32x4*)(ssq + (size_t)row * 16 + which * 8), b = *(const f32x4*)(ssq + (size_t)row * 16 + which * 8 + 4);
;     const float s = ((a[0] + a[1]) + (a[2] + a[3])) + ((b[0] + b[1]) + (b[2] + b[3])); return __builtin_amdgcn_rsqf(s * (1.f / 512.f) + EPS); }
;     DI void operator()(AccRef acc, const Unit& u, int wr, int wc, int fr, int fq) const {
;     ...
;             for (int m = 0; m < 4; ++m) { const int row = rowb + ai * 128 + m * 16; const float rs = row_rstd(ssq, row, 1); int b, key; row_bk(row, b, key);
; #pragma unroll
;                 for (int bj = 0; bj < 2; ++bj) {
;                     if (pn < 4) { *(u32x4*)(KN + (size_t)row * 1024 + 256 * pn + 128 * bj + 32 * wc + 8 * fq) = pk8(acc[ai][bj][m][0] * rs, acc[ai][bj][m][1] * rs); }
;                     else { const int h = 2 * (pn - 4) + bj;
; #pragma unroll
;                         for (int n = 0; n < 2; ++n) { bf16_t* dst = VT + ((size_t)((b * 8 + h) * 128 + 32 * wc + 8 * fq + 4 * n)) * KEYS + key;
; #pragma unroll
;                             for (int j = 0; j < 4; ++j) dst[(size_t)j * KEYS] = f2bf(acc[ai][bj][m][n][j] * rs); } } } }
.LBB0_883:
	v_add_u32_e32 v106, 32, v142
	v_ashrrev_i32_e32 v107, 31, v106
	v_lshlrev_b64 v[98:99], 6, v[106:107]
	v_lshl_add_u64 v[102:103], s[12:13], 0, v[98:99]
	s_nop 0
	s_movk_i32 s24, 0x3fdf
	v_cmp_lt_i32_e32 vcc, s24, v142
	s_and_saveexec_b64 s[24:25], vcc
	s_xor_b64 s[24:25], exec, s[24:25]
	v_add_u32_e32 v0, 0xffffc020, v142
	v_lshrrev_b32_e32 v108, 8, v0
	v_or_b32_sdwa v0, v106, s86 dst_sel:DWORD dst_unused:UNUSED_PAD src0_sel:BYTE_0 src1_sel:DWORD
	s_andn2_saveexec_b64 s[24:25], s[24:25]
	v_ashrrev_i32_e32 v108, 12, v106
	v_and_b32_e32 v0, 0xfff, v106
	s_or_b64 exec, exec, s[24:25]
	v_mov_b32_e32 v98, v210
	v_mov_b32_e32 v99, v211
	v_mov_b32_e32 v100, v212
	v_mov_b32_e32 v101, v213
	v_mov_b32_e32 v102, v214
	v_mov_b32_e32 v103, v215
	v_mov_b32_e32 v104, v216
	v_mov_b32_e32 v105, v217
	v_add_f32_e32 v102, v102, v103
	v_add_f32_e32 v103, v104, v105
	v_add_f32_e32 v98, v98, v99
	v_add_f32_e32 v99, v100, v101
	v_add_f32_e32 v102, v102, v103
	v_add_f32_e32 v98, v98, v99
	v_add_f32_e32 v98, v102, v98
	v_fmamk_f32 v98, v98, 0x3b000000, v193
	v_rsq_f32_e32 v98, v98
	v_lshl_add_u32 v104, v108, 10, v148
	s_mov_b64 s[24:25], -1
	s_and_b64 vcc, exec, s[4:5]
	v_lshl_add_u64 v[100:101], v[0:1], 1, s[14:15]
	s_cbranch_vccnz .LBB0_889
	v_lshl_add_u32 v0, s17, 7, v104
	v_mul_f32_e32 v99, v94, v98
	v_mad_i64_i32 v[102:103], s[24:25], v0, s85, v[100:101]
	v_cvt_pk_bf16_f32 v99, v99, s0
	global_store_short v[102:103], v99, off
	v_mul_f32_e32 v99, v95, v98
	v_add_co_u32_e32 v108, vcc, 0x2000, v102
	v_cvt_pk_bf16_f32 v99, v99, s0
	s_nop 0
	v_addc_co_u32_e32 v109, vcc, 0, v103, vcc
	global_store_short v[108:109], v99, off offset:512
	v_mul_f32_e32 v99, v96, v98
	v_add_co_u32_e32 v108, vcc, s72, v102
	v_cvt_pk_bf16_f32 v99, v99, s0
	s_nop 0
	v_addc_co_u32_e32 v109, vcc, 0, v103, vcc
	global_store_short v[108:109], v99, off offset:1024
	v_mul_f32_e32 v99, v97, v98
	v_add_co_u32_e32 v102, vcc, 0x6000, v102
	v_cvt_pk_bf16_f32 v99, v99, s0
	s_nop 0
	v_addc_co_u32_e32 v103, vcc, 0, v103, vcc
	v_or_b32_e32 v0, 4, v0
	global_store_short v[102:103], v99, off offset:1536
	v_mad_i64_i32 v[102:103], s[24:25], v0, s85, v[100:101]
	v_mul_f32_e32 v0, v90, v98
	v_cvt_pk_bf16_f32 v0, v0, s0
	global_store_short v[102:103], v0, off
	v_mul_f32_e32 v0, v91, v98
	v_add_co_u32_e32 v108, vcc, 0x2000, v102
	v_cvt_pk_bf16_f32 v0, v0, s0
	s_nop 0
	v_addc_co_u32_e32 v109, vcc, 0, v103, vcc
	global_store_short v[108:109], v0, off offset:512
	v_mul_f32_e32 v0, v92, v98
	v_add_co_u32_e32 v108, vcc, 0x4000, v102
	v_cvt_pk_bf16_f32 v0, v0, s0
	s_nop 0
	v_addc_co_u32_e32 v109, vcc, 0, v103, vcc
	global_store_short v[108:109], v0, off offset:1024
	v_mul_f32_e32 v0, v93, v98
	v_add_co_u32_e32 v102, vcc, 0x6000, v102
	v_cvt_pk_bf16_f32 v0, v0, s0
	s_nop 0
	v_addc_co_u32_e32 v103, vcc, 0, v103, vcc
	s_mov_b64 s[24:25], 0
	global_store_short v[102:103], v0, off offset:1536

; DI bf16_t f2bf(float a) { return (bf16_t)(pk2(a, 0.f) & 0xffffu); }
; DI u32x4 pk8(f32x4 a, f32x4 b) { u32x4 w; w.x = pk2(a[0], a[1]); w.y = pk2(a[2], a[3]); w.z = pk2(b[0], b[1]); w.w = pk2(b[2], b[3]); return w; }
; DI void row_bk(int row, int& b, int& key) { if (row < ML) { b = row >> 12; key = row & 4095; } else { const int rc = row - ML; b = rc >> 8; key = SEQ + (rc & 255); } }
; DI float row_rstd(const float* ssq, int row, int which) { const f32x4 a = *(const f32x4*)(ssq + (size_t)row * 16 + which * 8), b = *(const f32x4*)(ssq + (size_t)row * 16 + which * 8 + 4);
;     const float s = ((a[0] + a[1]) + (a[2] + a[3])) + ((b[0] + b[1]) + (b[2] + b[3])); return __builtin_amdgcn_rsqf(s * (1.f / 512.f) + EPS); }
;     DI void operator()(AccRef acc, const Unit& u, int wr, int wc, int fr, int fq) const {
;     ...
;             for (int m = 0; m < 4; ++m) { const int row = rowb + ai * 128 + m * 16; const float rs = row_rstd(ssq, row, 1); int b, key; row_bk(row, b, key);
; #pragma unroll
;                 for (int bj = 0; bj < 2; ++bj) {
;                     if (pn < 4) { *(u32x4*)(KN + (size_t)row * 1024 + 256 * pn + 128 * bj + 32 * wc + 8 * fq) = pk8(acc[ai][bj][m][0] * rs, acc[ai][bj][m][1] * rs); }
;                     else { const int h = 2 * (pn - 4) + bj;
; #pragma unroll
;                         for (int n = 0; n < 2; ++n) { bf16_t* dst = VT + ((size_t)((b * 8 + h) * 128 + 32 * wc + 8 * fq + 4 * n)) * KEYS + key;
; #pragma unroll
;                             for (int j = 0; j < 4; ++j) dst[(size_t)j * KEYS] = f2bf(acc[ai][bj][m][n][j] * rs); } } } }
.LBB0_893:
	v_add_u32_e32 v90, 48, v142
	v_ashrrev_i32_e32 v91, 31, v90
	v_lshlrev_b64 v[82:83], 6, v[90:91]
	v_lshl_add_u64 v[86:87], s[12:13], 0, v[82:83]
	s_nop 0
	s_movk_i32 s24, 0x3fcf
	v_cmp_lt_i32_e32 vcc, s24, v142
	s_and_saveexec_b64 s[24:25], vcc
	s_xor_b64 s[24:25], exec, s[24:25]
	v_add_u32_e32 v0, 0xffffc030, v142
	v_lshrrev_b32_e32 v92, 8, v0
	v_or_b32_sdwa v0, v90, s86 dst_sel:DWORD dst_unused:UNUSED_PAD src0_sel:BYTE_0 src1_sel:DWORD
	s_andn2_saveexec_b64 s[24:25], s[24:25]
	v_ashrrev_i32_e32 v92, 12, v90
	v_and_b32_e32 v0, 0xfff, v90
	s_or_b64 exec, exec, s[24:25]
	v_mov_b32_e32 v82, v218
	v_mov_b32_e32 v83, v219
	v_mov_b32_e32 v84, v220
	v_mov_b32_e32 v85, v221
	v_mov_b32_e32 v86, v222
	v_mov_b32_e32 v87, v223
	v_mov_b32_e32 v88, v224
	v_mov_b32_e32 v89, v225
	v_add_f32_e32 v86, v86, v87
	v_add_f32_e32 v87, v88, v89
	v_add_f32_e32 v82, v82, v83
	v_add_f32_e32 v83, v84, v85
	v_add_f32_e32 v86, v86, v87
	v_add_f32_e32 v82, v82, v83
	v_add_f32_e32 v82, v86, v82
	v_fmamk_f32 v82, v82, 0x3b000000, v193
	v_rsq_f32_e32 v82, v82
	v_lshl_add_u32 v88, v92, 10, v148
	s_mov_b64 s[24:25], -1
	s_and_b64 vcc, exec, s[4:5]
	v_lshl_add_u64 v[84:85], v[0:1], 1, s[14:15]
	s_cbranch_vccnz .LBB0_899
	v_lshl_add_u32 v0, s17, 7, v88
	v_mul_f32_e32 v83, v78, v82
	v_mad_i64_i32 v[86:87], s[24:25], v0, s85, v[84:85]
	v_cvt_pk_bf16_f32 v83, v83, s0
	global_store_short v[86:87], v83, off
	v_mul_f32_e32 v83, v79, v82
	v_add_co_u32_e32 v92, vcc, 0x2000, v86
	v_cvt_pk_bf16_f32 v83, v83, s0
	s_nop 0
	v_addc_co_u32_e32 v93, vcc, 0, v87, vcc
	global_store_short v[92:93], v83, off offset:512
	v_mul_f32_e32 v83, v80, v82
	v_add_co_u32_e32 v92, vcc, s72, v86
	v_cvt_pk_bf16_f32 v83, v83, s0
	s_nop 0
	v_addc_co_u32_e32 v93, vcc, 0, v87, vcc
	global_store_short v[92:93], v83, off offset:1024
	v_mul_f32_e32 v83, v81, v82
	v_add_co_u32_e32 v86, vcc, 0x6000, v86
	v_cvt_pk_bf16_f32 v83, v83, s0
	s_nop 0
	v_addc_co_u32_e32 v87, vcc, 0, v87, vcc
	v_or_b32_e32 v0, 4, v0
	global_store_short v[86:87], v83, off offset:1536
	v_mad_i64_i32 v[86:87], s[24:25], v0, s85, v[84:85]
	v_mul_f32_e32 v0, v74, v82
	v_cvt_pk_bf16_f32 v0, v0, s0
	global_store_short v[86:87], v0, off
	v_mul_f32_e32 v0, v75, v82
	v_add_co_u32_e32 v92, vcc, 0x2000, v86
	v_cvt_pk_bf16_f32 v0, v0, s0
	s_nop 0
	v_addc_co_u32_e32 v93, vcc, 0, v87, vcc
	global_store_short v[92:93], v0, off offset:512
	v_mul_f32_e32 v0, v76, v82
	v_add_co_u32_e32 v92, vcc, 0x4000, v86
	v_cvt_pk_bf16_f32 v0, v0, s0
	s_nop 0
	v_addc_co_u32_e32 v93, vcc, 0, v87, vcc
	global_store_short v[92:93], v0, off offset:1024
	v_mul_f32_e32 v0, v77, v82
	v_add_co_u32_e32 v86, vcc, 0x6000, v86
	v_cvt_pk_bf16_f32 v0, v0, s0
	s_nop 0
	v_addc_co_u32_e32 v87, vcc, 0, v87, vcc
	s_mov_b64 s[24:25], 0
	global_store_short v[86:87], v0, off offset:1536

; DI bf16_t f2bf(float a) { return (bf16_t)(pk2(a, 0.f) & 0xffffu); }
; DI u32x4 pk8(f32x4 a, f32x4 b) { u32x4 w; w.x = pk2(a[0], a[1]); w.y = pk2(a[2], a[3]); w.z = pk2(b[0], b[1]); w.w = pk2(b[2], b[3]); return w; }
; DI void row_bk(int row, int& b, int& key) { if (row < ML) { b = row >> 12; key = row & 4095; } else { const int rc = row - ML; b = rc >> 8; key = SEQ + (rc & 255); } }
; DI float row_rstd(const float* ssq, int row, int which) { const f32x4 a = *(const f32x4*)(ssq + (size_t)row * 16 + which * 8), b = *(const f32x4*)(ssq + (size_t)row * 16 + which * 8 + 4);
;     const float s = ((a[0] + a[1]) + (a[2] + a[3])) + ((b[0] + b[1]) + (b[2] + b[3])); return __builtin_amdgcn_rsqf(s * (1.f / 512.f) + EPS); }
;     DI void operator()(AccRef acc, const Unit& u, int wr, int wc, int fr, int fq) const {
;     ...
;             for (int m = 0; m < 4; ++m) { const int row = rowb + ai * 128 + m * 16; const float rs = row_rstd(ssq, row, 1); int b, key; row_bk(row, b, key);
; #pragma unroll
;                 for (int bj = 0; bj < 2; ++bj) {
;                     if (pn < 4) { *(u32x4*)(KN + (size_t)row * 1024 + 256 * pn + 128 * bj + 32 * wc + 8 * fq) = pk8(acc[ai][bj][m][0] * rs, acc[ai][bj][m][1] * rs); }
;                     else { const int h = 2 * (pn - 4) + bj;
; #pragma unroll
;                         for (int n = 0; n < 2; ++n) { bf16_t* dst = VT + ((size_t)((b * 8 + h) * 128 + 32 * wc + 8 * fq + 4 * n)) * KEYS + key;
; #pragma unroll
;                             for (int j = 0; j < 4; ++j) dst[(size_t)j * KEYS] = f2bf(acc[ai][bj][m][n][j] * rs); } } } }
.LBB0_903:
	v_add_u32_e32 v74, 0x80, v142
	v_ashrrev_i32_e32 v75, 31, v74
	v_lshlrev_b64 v[66:67], 6, v[74:75]
	v_lshl_add_u64 v[70:71], s[12:13], 0, v[66:67]
	s_nop 0
	s_movk_i32 s24, 0x3f7f
	v_cmp_lt_i32_e32 vcc, s24, v142
	s_and_saveexec_b64 s[24:25], vcc
	s_xor_b64 s[24:25], exec, s[24:25]
	v_add_u32_e32 v0, 0xffffc080, v142
	v_lshrrev_b32_e32 v76, 8, v0
	v_or_b32_sdwa v0, v74, s86 dst_sel:DWORD dst_unused:UNUSED_PAD src0_sel:BYTE_0 src1_sel:DWORD
	s_andn2_saveexec_b64 s[24:25], s[24:25]
	v_ashrrev_i32_e32 v76, 12, v74
	v_and_b32_e32 v0, 0xfff, v74
	s_or_b64 exec, exec, s[24:25]
	v_mov_b32_e32 v66, v226
	v_mov_b32_e32 v67, v227
	v_mov_b32_e32 v68, v228
	v_mov_b32_e32 v69, v229
	v_mov_b32_e32 v70, v230
	v_mov_b32_e32 v71, v231
	v_mov_b32_e32 v72, v232
	v_mov_b32_e32 v73, v233
	v_add_f32_e32 v70, v70, v71
	v_add_f32_e32 v71, v72, v73
	v_add_f32_e32 v66, v66, v67
	v_add_f32_e32 v67, v68, v69
	v_add_f32_e32 v70, v70, v71
	v_add_f32_e32 v66, v66, v67
	v_add_f32_e32 v66, v70, v66
	v_fmamk_f32 v66, v66, 0x3b000000, v193
	v_rsq_f32_e32 v66, v66
	v_lshl_add_u32 v72, v76, 10, v148
	s_mov_b64 s[24:25], -1
	s_and_b64 vcc, exec, s[4:5]
	v_lshl_add_u64 v[68:69], v[0:1], 1, s[14:15]
	s_cbranch_vccnz .LBB0_909
	v_lshl_add_u32 v0, s17, 7, v72
	v_mul_f32_e32 v67, v62, v66
	v_mad_i64_i32 v[70:71], s[24:25], v0, s85, v[68:69]
	v_cvt_pk_bf16_f32 v67, v67, s0
	global_store_short v[70:71], v67, off
	v_mul_f32_e32 v67, v63, v66
	v_add_co_u32_e32 v76, vcc, 0x2000, v70
	v_cvt_pk_bf16_f32 v67, v67, s0
	s_nop 0
	v_addc_co_u32_e32 v77, vcc, 0, v71, vcc
	global_store_short v[76:77], v67, off offset:512
	v_mul_f32_e32 v67, v64, v66
	v_add_co_u32_e32 v76, vcc, s72, v70
	v_cvt_pk_bf16_f32 v67, v67, s0
	s_nop 0
	v_addc_co_u32_e32 v77, vcc, 0, v71, vcc
	global_store_short v[76:77], v67, off offset:1024
	v_mul_f32_e32 v67, v65, v66
	v_add_co_u32_e32 v70, vcc, 0x6000, v70
	v_cvt_pk_bf16_f32 v67, v67, s0
	s_nop 0
	v_addc_co_u32_e32 v71, vcc, 0, v71, vcc
	v_or_b32_e32 v0, 4, v0
	global_store_short v[70:71], v67, off offset:1536
	v_mad_i64_i32 v[70:71], s[24:25], v0, s85, v[68:69]
	v_mul_f32_e32 v0, v58, v66
	v_cvt_pk_bf16_f32 v0, v0, s0
	global_store_short v[70:71], v0, off
	v_mul_f32_e32 v0, v59, v66
	v_add_co_u32_e32 v76, vcc, 0x2000, v70
	v_cvt_pk_bf16_f32 v0, v0, s0
	s_nop 0
	v_addc_co_u32_e32 v77, vcc, 0, v71, vcc
	global_store_short v[76:77], v0, off offset:512
	v_mul_f32_e32 v0, v60, v66
	v_add_co_u32_e32 v76, vcc, 0x4000, v70
	v_cvt_pk_bf16_f32 v0, v0, s0
	s_nop 0
	v_addc_co_u32_e32 v77, vcc, 0, v71, vcc
	global_store_short v[76:77], v0, off offset:1024
	v_mul_f32_e32 v0, v61, v66
	v_add_co_u32_e32 v70, vcc, 0x6000, v70
	v_cvt_pk_bf16_f32 v0, v0, s0
	s_nop 0
	v_addc_co_u32_e32 v71, vcc, 0, v71, vcc
	s_mov_b64 s[24:25], 0
	global_store_short v[70:71], v0, off offset:1536

; DI bf16_t f2bf(float a) { return (bf16_t)(pk2(a, 0.f) & 0xffffu); }
; DI u32x4 pk8(f32x4 a, f32x4 b) { u32x4 w; w.x = pk2(a[0], a[1]); w.y = pk2(a[2], a[3]); w.z = pk2(b[0], b[1]); w.w = pk2(b[2], b[3]); return w; }
; DI void row_bk(int row, int& b, int& key) { if (row < ML) { b = row >> 12; key = row & 4095; } else { const int rc = row - ML; b = rc >> 8; key = SEQ + (rc & 255); } }
; DI float row_rstd(const float* ssq, int row, int which) { const f32x4 a = *(const f32x4*)(ssq + (size_t)row * 16 + which * 8), b = *(const f32x4*)(ssq + (size_t)row * 16 + which * 8 + 4);
;     const float s = ((a[0] + a[1]) + (a[2] + a[3])) + ((b[0] + b[1]) + (b[2] + b[3])); return __builtin_amdgcn_rsqf(s * (1.f / 512.f) + EPS); }
;     DI void operator()(AccRef acc, const Unit& u, int wr, int wc, int fr, int fq) const {
;     ...
;             for (int m = 0; m < 4; ++m) { const int row = rowb + ai * 128 + m * 16; const float rs = row_rstd(ssq, row, 1); int b, key; row_bk(row, b, key);
; #pragma unroll
;                 for (int bj = 0; bj < 2; ++bj) {
;                     if (pn < 4) { *(u32x4*)(KN + (size_t)row * 1024 + 256 * pn + 128 * bj + 32 * wc + 8 * fq) = pk8(acc[ai][bj][m][0] * rs, acc[ai][bj][m][1] * rs); }
;                     else { const int h = 2 * (pn - 4) + bj;
; #pragma unroll
;                         for (int n = 0; n < 2; ++n) { bf16_t* dst = VT + ((size_t)((b * 8 + h) * 128 + 32 * wc + 8 * fq + 4 * n)) * KEYS + key;
; #pragma unroll
;                             for (int j = 0; j < 4; ++j) dst[(size_t)j * KEYS] = f2bf(acc[ai][bj][m][n][j] * rs); } } } }
.LBB0_913:
	v_add_u32_e32 v58, 0x90, v142
	v_ashrrev_i32_e32 v59, 31, v58
	v_lshlrev_b64 v[50:51], 6, v[58:59]
	v_lshl_add_u64 v[54:55], s[12:13], 0, v[50:51]
	s_nop 0
	s_movk_i32 s24, 0x3f6f
	v_cmp_lt_i32_e32 vcc, s24, v142
	s_and_saveexec_b64 s[24:25], vcc
	s_xor_b64 s[24:25], exec, s[24:25]
	v_add_u32_e32 v0, 0xffffc090, v142
	v_lshrrev_b32_e32 v60, 8, v0
	v_or_b32_sdwa v0, v58, s86 dst_sel:DWORD dst_unused:UNUSED_PAD src0_sel:BYTE_0 src1_sel:DWORD
	s_andn2_saveexec_b64 s[24:25], s[24:25]
	v_ashrrev_i32_e32 v60, 12, v58
	v_and_b32_e32 v0, 0xfff, v58
	s_or_b64 exec, exec, s[24:25]
	v_mov_b32_e32 v50, v234
	v_mov_b32_e32 v51, v235
	v_mov_b32_e32 v52, v236
	v_mov_b32_e32 v53, v237
	v_mov_b32_e32 v54, v238
	v_mov_b32_e32 v55, v239
	v_mov_b32_e32 v56, v240
	v_mov_b32_e32 v57, v241
	v_add_f32_e32 v54, v54, v55
	v_add_f32_e32 v55, v56, v57
	v_add_f32_e32 v50, v50, v51
	v_add_f32_e32 v51, v52, v53
	v_add_f32_e32 v54, v54, v55
	v_add_f32_e32 v50, v50, v51
	v_add_f32_e32 v50, v54, v50
	v_fmamk_f32 v50, v50, 0x3b000000, v193
	v_rsq_f32_e32 v50, v50
	v_lshl_add_u32 v56, v60, 10, v148
	s_mov_b64 s[24:25], -1
	s_and_b64 vcc, exec, s[4:5]
	v_lshl_add_u64 v[52:53], v[0:1], 1, s[14:15]
	s_cbranch_vccnz .LBB0_919
	v_lshl_add_u32 v0, s17, 7, v56
	v_mul_f32_e32 v51, v46, v50
	v_mad_i64_i32 v[54:55], s[24:25], v0, s85, v[52:53]
	v_cvt_pk_bf16_f32 v51, v51, s0
	global_store_short v[54:55], v51, off
	v_mul_f32_e32 v51, v47, v50
	v_add_co_u32_e32 v60, vcc, 0x2000, v54
	v_cvt_pk_bf16_f32 v51, v51, s0
	s_nop 0
	v_addc_co_u32_e32 v61, vcc, 0, v55, vcc
	global_store_short v[60:61], v51, off offset:512
	v_mul_f32_e32 v51, v48, v50
	v_add_co_u32_e32 v60, vcc, s72, v54
	v_cvt_pk_bf16_f32 v51, v51, s0
	s_nop 0
	v_addc_co_u32_e32 v61, vcc, 0, v55, vcc
	global_store_short v[60:61], v51, off offset:1024
	v_mul_f32_e32 v51, v49, v50
	v_add_co_u32_e32 v54, vcc, 0x6000, v54
	v_cvt_pk_bf16_f32 v51, v51, s0
	s_nop 0
	v_addc_co_u32_e32 v55, vcc, 0, v55, vcc
	v_or_b32_e32 v0, 4, v0
	global_store_short v[54:55], v51, off offset:1536
	v_mad_i64_i32 v[54:55], s[24:25], v0, s85, v[52:53]
	v_mul_f32_e32 v0, v42, v50
	v_cvt_pk_bf16_f32 v0, v0, s0
	global_store_short v[54:55], v0, off
	v_mul_f32_e32 v0, v43, v50
	v_add_co_u32_e32 v60, vcc, 0x2000, v54
	v_cvt_pk_bf16_f32 v0, v0, s0
	s_nop 0
	v_addc_co_u32_e32 v61, vcc, 0, v55, vcc
	global_store_short v[60:61], v0, off offset:512
	v_mul_f32_e32 v0, v44, v50
	v_add_co_u32_e32 v60, vcc, 0x4000, v54
	v_cvt_pk_bf16_f32 v0, v0, s0
	s_nop 0
	v_addc_co_u32_e32 v61, vcc, 0, v55, vcc
	global_store_short v[60:61], v0, off offset:1024
	v_mul_f32_e32 v0, v45, v50
	v_add_co_u32_e32 v54, vcc, 0x6000, v54
	v_cvt_pk_bf16_f32 v0, v0, s0
	s_nop 0
	v_addc_co_u32_e32 v55, vcc, 0, v55, vcc
	s_mov_b64 s[24:25], 0
	global_store_short v[54:55], v0, off offset:1536

; DI bf16_t f2bf(float a) { return (bf16_t)(pk2(a, 0.f) & 0xffffu); }
; DI u32x4 pk8(f32x4 a, f32x4 b) { u32x4 w; w.x = pk2(a[0], a[1]); w.y = pk2(a[2], a[3]); w.z = pk2(b[0], b[1]); w.w = pk2(b[2], b[3]); return w; }
; DI void row_bk(int row, int& b, int& key) { if (row < ML) { b = row >> 12; key = row & 4095; } else { const int rc = row - ML; b = rc >> 8; key = SEQ + (rc & 255); } }
; DI float row_rstd(const float* ssq, int row, int which) { const f32x4 a = *(const f32x4*)(ssq + (size_t)row * 16 + which * 8), b = *(const f32x4*)(ssq + (size_t)row * 16 + which * 8 + 4);
;     const float s = ((a[0] + a[1]) + (a[2] + a[3])) + ((b[0] + b[1]) + (b[2] + b[3])); return __builtin_amdgcn_rsqf(s * (1.f / 512.f) + EPS); }
;     DI void operator()(AccRef acc, const Unit& u, int wr, int wc, int fr, int fq) const {
;     ...
;             for (int m = 0; m < 4; ++m) { const int row = rowb + ai * 128 + m * 16; const float rs = row_rstd(ssq, row, 1); int b, key; row_bk(row, b, key);
; #pragma unroll
;                 for (int bj = 0; bj < 2; ++bj) {
;                     if (pn < 4) { *(u32x4*)(KN + (size_t)row * 1024 + 256 * pn + 128 * bj + 32 * wc + 8 * fq) = pk8(acc[ai][bj][m][0] * rs, acc[ai][bj][m][1] * rs); }
;                     else { const int h = 2 * (pn - 4) + bj;
; #pragma unroll
;                         for (int n = 0; n < 2; ++n) { bf16_t* dst = VT + ((size_t)((b * 8 + h) * 128 + 32 * wc + 8 * fq + 4 * n)) * KEYS + key;
; #pragma unroll
;                             for (int j = 0; j < 4; ++j) dst[(size_t)j * KEYS] = f2bf(acc[ai][bj][m][n][j] * rs); } } } }
.LBB0_923:
	v_add_u32_e32 v42, 0xa0, v142
	v_ashrrev_i32_e32 v43, 31, v42
	v_lshlrev_b64 v[34:35], 6, v[42:43]
	v_lshl_add_u64 v[38:39], s[12:13], 0, v[34:35]
	s_nop 0
	s_movk_i32 s24, 0x3f5f
	v_cmp_lt_i32_e32 vcc, s24, v142
	s_and_saveexec_b64 s[24:25], vcc
	s_xor_b64 s[24:25], exec, s[24:25]
	v_add_u32_e32 v0, 0xffffc0a0, v142
	v_lshrrev_b32_e32 v44, 8, v0
	v_or_b32_sdwa v0, v42, s86 dst_sel:DWORD dst_unused:UNUSED_PAD src0_sel:BYTE_0 src1_sel:DWORD
	s_andn2_saveexec_b64 s[24:25], s[24:25]
	v_ashrrev_i32_e32 v44, 12, v42
	v_and_b32_e32 v0, 0xfff, v42
	s_or_b64 exec, exec, s[24:25]
	v_mov_b32_e32 v34, v242
	v_mov_b32_e32 v35, v243
	v_mov_b32_e32 v36, v244
	v_mov_b32_e32 v37, v245
	v_mov_b32_e32 v38, v246
	v_mov_b32_e32 v39, v247
	v_mov_b32_e32 v40, v248
	v_mov_b32_e32 v41, v249
	v_add_f32_e32 v38, v38, v39
	v_add_f32_e32 v39, v40, v41
	v_add_f32_e32 v34, v34, v35
	v_add_f32_e32 v35, v36, v37
	v_add_f32_e32 v38, v38, v39
	v_add_f32_e32 v34, v34, v35
	v_add_f32_e32 v34, v38, v34
	v_fmamk_f32 v34, v34, 0x3b000000, v193
	v_rsq_f32_e32 v34, v34
	v_lshl_add_u32 v40, v44, 10, v148
	s_mov_b64 s[24:25], -1
	s_and_b64 vcc, exec, s[4:5]
	v_lshl_add_u64 v[36:37], v[0:1], 1, s[14:15]
	s_cbranch_vccnz .LBB0_929
	v_lshl_add_u32 v0, s17, 7, v40
	v_mul_f32_e32 v35, v30, v34
	v_mad_i64_i32 v[38:39], s[24:25], v0, s85, v[36:37]
	v_cvt_pk_bf16_f32 v35, v35, s0
	global_store_short v[38:39], v35, off
	v_mul_f32_e32 v35, v31, v34
	v_add_co_u32_e32 v44, vcc, 0x2000, v38
	v_cvt_pk_bf16_f32 v35, v35, s0
	s_nop 0
	v_addc_co_u32_e32 v45, vcc, 0, v39, vcc
	global_store_short v[44:45], v35, off offset:512
	v_mul_f32_e32 v35, v32, v34
	v_add_co_u32_e32 v44, vcc, s72, v38
	v_cvt_pk_bf16_f32 v35, v35, s0
	s_nop 0
	v_addc_co_u32_e32 v45, vcc, 0, v39, vcc
	global_store_short v[44:45], v35, off offset:1024
	v_mul_f32_e32 v35, v33, v34
	v_add_co_u32_e32 v38, vcc, 0x6000, v38
	v_cvt_pk_bf16_f32 v35, v35, s0
	s_nop 0
	v_addc_co_u32_e32 v39, vcc, 0, v39, vcc
	v_or_b32_e32 v0, 4, v0
	global_store_short v[38:39], v35, off offset:1536
	v_mad_i64_i32 v[38:39], s[24:25], v0, s85, v[36:37]
	v_mul_f32_e32 v0, v26, v34
	v_cvt_pk_bf16_f32 v0, v0, s0
	global_store_short v[38:39], v0, off
	v_mul_f32_e32 v0, v27, v34
	v_add_co_u32_e32 v44, vcc, 0x2000, v38
	v_cvt_pk_bf16_f32 v0, v0, s0
	s_nop 0
	v_addc_co_u32_e32 v45, vcc, 0, v39, vcc
	global_store_short v[44:45], v0, off offset:512
	v_mul_f32_e32 v0, v28, v34
	v_add_co_u32_e32 v44, vcc, 0x4000, v38
	v_cvt_pk_bf16_f32 v0, v0, s0
	s_nop 0
	v_addc_co_u32_e32 v45, vcc, 0, v39, vcc
	global_store_short v[44:45], v0, off offset:1024
	v_mul_f32_e32 v0, v29, v34
	v_add_co_u32_e32 v38, vcc, 0x6000, v38
	v_cvt_pk_bf16_f32 v0, v0, s0
	s_nop 0
	v_addc_co_u32_e32 v39, vcc, 0, v39, vcc
	s_mov_b64 s[24:25], 0
	global_store_short v[38:39], v0, off offset:1536

; DI bf16_t f2bf(float a) { return (bf16_t)(pk2(a, 0.f) & 0xffffu); }
; DI u32x4 pk8(f32x4 a, f32x4 b) { u32x4 w; w.x = pk2(a[0], a[1]); w.y = pk2(a[2], a[3]); w.z = pk2(b[0], b[1]); w.w = pk2(b[2], b[3]); return w; }
; DI void row_bk(int row, int& b, int& key) { if (row < ML) { b = row >> 12; key = row & 4095; } else { const int rc = row - ML; b = rc >> 8; key = SEQ + (rc & 255); } }
; DI float row_rstd(const float* ssq, int row, int which) { const f32x4 a = *(const f32x4*)(ssq + (size_t)row * 16 + which * 8), b = *(const f32x4*)(ssq + (size_t)row * 16 + which * 8 + 4);
;     const float s = ((a[0] + a[1]) + (a[2] + a[3])) + ((b[0] + b[1]) + (b[2] + b[3])); return __builtin_amdgcn_rsqf(s * (1.f / 512.f) + EPS); }
;     DI void operator()(AccRef acc, const Unit& u, int wr, int wc, int fr, int fq) const {
;     ...
;             for (int m = 0; m < 4; ++m) { const int row = rowb + ai * 128 + m * 16; const float rs = row_rstd(ssq, row, 1); int b, key; row_bk(row, b, key);
; #pragma unroll
;                 for (int bj = 0; bj < 2; ++bj) {
;                     if (pn < 4) { *(u32x4*)(KN + (size_t)row * 1024 + 256 * pn + 128 * bj + 32 * wc + 8 * fq) = pk8(acc[ai][bj][m][0] * rs, acc[ai][bj][m][1] * rs); }
;                     else { const int h = 2 * (pn - 4) + bj;
; #pragma unroll
;                         for (int n = 0; n < 2; ++n) { bf16_t* dst = VT + ((size_t)((b * 8 + h) * 128 + 32 * wc + 8 * fq + 4 * n)) * KEYS + key;
; #pragma unroll
;                             for (int j = 0; j < 4; ++j) dst[(size_t)j * KEYS] = f2bf(acc[ai][bj][m][n][j] * rs); } } } }
.LBB0_933:
	v_add_u32_e32 v26, 0xb0, v142
	v_ashrrev_i32_e32 v27, 31, v26
	v_lshlrev_b64 v[18:19], 6, v[26:27]
	v_lshl_add_u64 v[22:23], s[12:13], 0, v[18:19]
	s_nop 0
	s_movk_i32 s24, 0x3f4f
	v_cmp_lt_i32_e32 vcc, s24, v142
	s_and_saveexec_b64 s[24:25], vcc
	s_xor_b64 s[24:25], exec, s[24:25]
	v_add_u32_e32 v0, 0xffffc0b0, v142
	v_lshrrev_b32_e32 v28, 8, v0
	v_or_b32_sdwa v0, v26, s86 dst_sel:DWORD dst_unused:UNUSED_PAD src0_sel:BYTE_0 src1_sel:DWORD
	s_andn2_saveexec_b64 s[24:25], s[24:25]
	v_ashrrev_i32_e32 v28, 12, v26
	v_and_b32_e32 v0, 0xfff, v26
	s_or_b64 exec, exec, s[24:25]
	v_mov_b32_e32 v18, v250
	v_mov_b32_e32 v19, v251
	v_mov_b32_e32 v20, v252
	v_mov_b32_e32 v21, v253
	v_mov_b32_e32 v22, v166
	v_mov_b32_e32 v23, v167
	v_mov_b32_e32 v24, v168
	v_mov_b32_e32 v25, v169
	v_add_f32_e32 v22, v22, v23
	v_add_f32_e32 v23, v24, v25
	v_add_f32_e32 v18, v18, v19
	v_add_f32_e32 v19, v20, v21
	v_add_f32_e32 v22, v22, v23
	v_add_f32_e32 v18, v18, v19
	v_add_f32_e32 v18, v22, v18
	v_fmamk_f32 v18, v18, 0x3b000000, v193
	v_rsq_f32_e32 v18, v18
	v_lshl_add_u32 v24, v28, 10, v148
	s_mov_b64 s[24:25], -1
	s_and_b64 vcc, exec, s[4:5]
	v_lshl_add_u64 v[20:21], v[0:1], 1, s[14:15]
	s_cbranch_vccnz .LBB0_939
	v_lshl_add_u32 v0, s17, 7, v24
	v_mul_f32_e32 v19, v14, v18
	v_mad_i64_i32 v[22:23], s[24:25], v0, s85, v[20:21]
	v_cvt_pk_bf16_f32 v19, v19, s0
	global_store_short v[22:23], v19, off
	v_mul_f32_e32 v19, v15, v18
	v_add_co_u32_e32 v28, vcc, 0x2000, v22
	v_cvt_pk_bf16_f32 v19, v19, s0
	s_nop 0
	v_addc_co_u32_e32 v29, vcc, 0, v23, vcc
	global_store_short v[28:29], v19, off offset:512
	v_mul_f32_e32 v19, v16, v18
	v_add_co_u32_e32 v28, vcc, s72, v22
	v_cvt_pk_bf16_f32 v19, v19, s0
	s_nop 0
	v_addc_co_u32_e32 v29, vcc, 0, v23, vcc
	global_store_short v[28:29], v19, off offset:1024
	v_mul_f32_e32 v19, v17, v18
	v_add_co_u32_e32 v22, vcc, 0x6000, v22
	v_cvt_pk_bf16_f32 v19, v19, s0
	s_nop 0
	v_addc_co_u32_e32 v23, vcc, 0, v23, vcc
	v_or_b32_e32 v0, 4, v0
	global_store_short v[22:23], v19, off offset:1536
	v_mad_i64_i32 v[22:23], s[24:25], v0, s85, v[20:21]
	v_mul_f32_e32 v0, v10, v18
	v_cvt_pk_bf16_f32 v0, v0, s0
	global_store_short v[22:23], v0, off
	v_mul_f32_e32 v0, v11, v18
	v_add_co_u32_e32 v28, vcc, 0x2000, v22
	v_cvt_pk_bf16_f32 v0, v0, s0
	s_nop 0
	v_addc_co_u32_e32 v29, vcc, 0, v23, vcc
	global_store_short v[28:29], v0, off offset:512
	v_mul_f32_e32 v0, v12, v18
	v_add_co_u32_e32 v28, vcc, 0x4000, v22
	v_cvt_pk_bf16_f32 v0, v0, s0
	s_nop 0
	v_addc_co_u32_e32 v29, vcc, 0, v23, vcc
	global_store_short v[28:29], v0, off offset:1024
	v_mul_f32_e32 v0, v13, v18
	v_add_co_u32_e32 v22, vcc, 0x6000, v22
	v_cvt_pk_bf16_f32 v0, v0, s0
	s_nop 0
	v_addc_co_u32_e32 v23, vcc, 0, v23, vcc
	s_mov_b64 s[24:25], 0
	global_store_short v[22:23], v0, off offset:1536
